# attention tile loop VALU trims: shift test hoisted per unit, K LDS address invariant hoisted (v_add instead of lshl_add+mad_u64), table selection without dead selects/adds, mul_u32_u24 for the div-by-
# speedup vs baseline: 1.0015x; 1.0015x over previous
; #define LAS __attribute__((address_space(3)))
; __device__ __forceinline__ void attn_unit(const AttnP& P, LAS unsigned char* lds, int b, int hd, int qq, int wave, int lane) {
;     int tid_ = threadIdx.x; asm volatile("" : "+v"(tid_));
;     const int hb = b * 8 + hd, tid = tid_;
;     float shift;
;     { const float mq = wave_max(fabsf(P.gq[lane])), mk = wave_max(fabsf(P.gk[lane])); shift = fminf(8.0f * mq * mk * 1.4426950408889634f, 64.0f); shift = shift > 30.0f ? shift : 0.f; }
;     {
;         u32x4 kr[8], vr[8];
; #pragma unroll
;         for (int j = 0; j < 8; ++j) { const int chunk = tid + 512 * j, row = chunk >> 3, piece = chunk & 7, cls = row >> 5, il = row & 31;
;             kr[j] = *(const u32x4*)(P.K + ((size_t)(hb * 16 + cls) * 128 + 32 * qq + il) * 64 + piece * 8); }
; #pragma unroll
;         for (int j = 0; j < 8; ++j) { const int chunk = tid + 512 * j, cls = chunk >> 8, within = chunk & 255;
;             vr[j] = *(const u32x4*)(P.Vt + ((size_t)(hb * 16 + cls) * 16 + 4 * qq) * 512 + within * 8); }
;         __syncthreads();
.LBB0_169:
	v_mov_b32_e32 v1, v0
	global_load_dword v32, v[192:193], off
	global_load_dword v33, v[194:195], off
	v_cmp_lt_i32_e32 vcc, v217, v216
	s_bfe_u32 s18, s97, 0x40004
	s_and_b32 s98, s97, 7
	v_cndmask_b32_e32 v2, v215, v217, vcc
	v_cmp_lt_i32_e32 vcc, v218, v216
	s_lshl_b32 s0, s18, 3
	s_or_b32 s0, s0, s98
	v_cndmask_b32_e32 v3, v215, v218, vcc
	v_cmp_lt_i32_e32 vcc, v219, v216
	v_add_u32_e32 v70, 0x200, v1
	v_add_u32_e32 v71, 0x400, v1
	v_cndmask_b32_e32 v4, v215, v219, vcc
	v_cmp_lt_i32_e32 vcc, v220, v216
	v_lshlrev_b32_e32 v223, 2, v4
	s_lshl_b32 s99, s0, 4
	v_cndmask_b32_e32 v5, v215, v220, vcc
	v_ashrrev_i32_e32 v4, 8, v70
	s_bfe_u32 s12, s97, 0x10003
	v_lshlrev_b32_e32 v199, 2, v5
	v_lshlrev_b32_e32 v67, 4, v1
	v_ashrrev_i32_e32 v5, 8, v71
	v_add_u32_e32 v4, s99, v4
	s_xor_b32 s1, s12, 3
	v_and_b32_e32 v190, 0x70, v67
	v_add_u32_e32 v6, s99, v5
	v_ashrrev_i32_e32 v5, 31, v4
	v_lshlrev_b32_e32 v224, 2, v3
	s_lshl_b32 s4, s1, 12
	v_and_b32_e32 v3, 0xf80, v67
	v_lshl_add_u64 v[28:29], s[50:51], 0, v[190:191]
	v_lshlrev_b64 v[36:37], 14, v[4:5]
	v_mov_b32_e32 v27, v191
	v_or_b32_e32 v26, s4, v3
	v_lshl_add_u64 v[4:5], v[28:29], 0, v[36:37]
	v_lshlrev_b32_e32 v225, 2, v2
	v_ashrrev_i32_e32 v2, 8, v1
	v_add_u32_e32 v72, 0x600, v1
	v_add_u32_e32 v73, 0x800, v1
	v_add_u32_e32 v74, 0xa00, v1
	v_add_u32_e32 v75, 0xc00, v1
	v_lshl_add_u64 v[16:17], v[4:5], 0, v[26:27]
	v_ashrrev_i32_e32 v7, 8, v72
	v_ashrrev_i32_e32 v9, 8, v73
	v_ashrrev_i32_e32 v11, 8, v74
	v_ashrrev_i32_e32 v13, 8, v75
	v_add_u32_e32 v2, s99, v2
	v_add_u32_e32 v8, s99, v7
	v_add_u32_e32 v10, s99, v9
	v_add_u32_e32 v12, s99, v11
	v_add_u32_e32 v14, s99, v13
	v_ashrrev_i32_e32 v3, 31, v2
	v_ashrrev_i32_e32 v7, 31, v6
	v_ashrrev_i32_e32 v9, 31, v8
	v_ashrrev_i32_e32 v11, 31, v10
	v_ashrrev_i32_e32 v13, 31, v12
	v_ashrrev_i32_e32 v15, 31, v14
	v_lshlrev_b64 v[34:35], 14, v[2:3]
	v_lshlrev_b64 v[42:43], 14, v[6:7]
	v_lshlrev_b64 v[44:45], 14, v[8:9]
	v_lshlrev_b64 v[50:51], 14, v[10:11]
	v_lshlrev_b64 v[52:53], 14, v[12:13]
	v_lshlrev_b64 v[58:59], 14, v[14:15]
	v_lshl_add_u64 v[2:3], v[28:29], 0, v[34:35]
	v_lshl_add_u64 v[6:7], v[28:29], 0, v[42:43]
	v_lshl_add_u64 v[8:9], v[28:29], 0, v[44:45]
	v_lshl_add_u64 v[10:11], v[28:29], 0, v[50:51]
	v_lshl_add_u64 v[12:13], v[28:29], 0, v[52:53]
	v_lshl_add_u64 v[14:15], v[28:29], 0, v[58:59]
	v_lshl_add_u64 v[2:3], v[2:3], 0, v[26:27]
	v_lshl_add_u64 v[18:19], v[6:7], 0, v[26:27]
	v_lshl_add_u64 v[20:21], v[8:9], 0, v[26:27]
	v_lshl_add_u64 v[22:23], v[10:11], 0, v[26:27]
	v_lshl_add_u64 v[24:25], v[12:13], 0, v[26:27]
	v_lshl_add_u64 v[30:31], v[14:15], 0, v[26:27]
	v_add_u32_e32 v76, 0xe00, v1
	v_ashrrev_i32_e32 v38, 8, v76
	s_add_u32 s4, s52, s4
	s_addc_u32 s5, s53, 0
	s_waitcnt vmcnt(1)
	v_and_b32_e32 v4, 0x7fffffff, v32
	ds_bpermute_b32 v39, v225, v4
	global_load_dwordx4 v[2:5], v[2:3], off
	s_nop 0
	global_load_dwordx4 v[6:9], v[16:17], off
	global_load_dwordx4 v[10:13], v[18:19], off
	s_nop 0
	global_load_dwordx4 v[14:17], v[20:21], off
	v_max_f32_e64 v18, |v32|, |v32|
	s_waitcnt vmcnt(4)
	v_and_b32_e32 v40, 0x7fffffff, v33
	ds_bpermute_b32 v40, v225, v40
	s_waitcnt lgkmcnt(1)
	v_max_f32_e32 v19, v39, v39
	v_max_f32_e32 v32, v18, v19
	ds_bpermute_b32 v39, v224, v32
	v_max_f32_e64 v33, |v33|, |v33|
	s_waitcnt lgkmcnt(1)
	v_max_f32_e32 v40, v40, v40
	v_max_f32_e32 v66, v33, v40
	global_load_dwordx4 v[18:21], v[22:23], off
	s_nop 0
	global_load_dwordx4 v[22:25], v[24:25], off
	s_waitcnt lgkmcnt(0)
	v_max_f32_e32 v39, v39, v39
	v_max_f32_e32 v32, v32, v39
	ds_bpermute_b32 v39, v223, v32
	ds_bpermute_b32 v68, v224, v66
	v_cmp_lt_i32_e32 vcc, v221, v216
	v_lshrrev_b32_e32 v1, 3, v1
	v_mov_b32_e32 v228, v201
	s_waitcnt lgkmcnt(1)
	v_max_f32_e32 v33, v39, v39
	v_max_f32_e32 v69, v32, v33
	v_add_u32_e32 v32, s99, v38
	v_ashrrev_i32_e32 v33, 31, v32
	v_lshlrev_b64 v[60:61], 14, v[32:33]
	v_and_b32_e32 v38, 0xff0, v67
	v_mov_b32_e32 v39, v191
	v_lshl_add_u64 v[28:29], v[28:29], 0, v[60:61]
	v_lshl_add_u64 v[62:63], s[4:5], 0, v[38:39]
	v_lshl_add_u64 v[32:33], v[28:29], 0, v[26:27]
	v_lshl_add_u64 v[34:35], v[62:63], 0, v[34:35]
	v_lshl_add_u64 v[38:39], v[62:63], 0, v[36:37]
	v_lshl_add_u64 v[42:43], v[62:63], 0, v[42:43]
	v_lshl_add_u64 v[46:47], v[62:63], 0, v[44:45]
	v_lshl_add_u64 v[50:51], v[62:63], 0, v[50:51]
	v_lshl_add_u64 v[54:55], v[62:63], 0, v[52:53]
	v_lshl_add_u64 v[58:59], v[62:63], 0, v[58:59]
	v_lshl_add_u64 v[62:63], v[62:63], 0, v[60:61]
	global_load_dwordx4 v[26:29], v[30:31], off
	s_nop 0
	global_load_dwordx4 v[30:33], v[32:33], off
	s_nop 0
	global_load_dwordx4 v[34:37], v[34:35], off
	s_nop 0
	global_load_dwordx4 v[38:41], v[38:39], off
	s_nop 0
	global_load_dwordx4 v[42:45], v[42:43], off
	s_nop 0
	global_load_dwordx4 v[46:49], v[46:47], off
	s_nop 0
	global_load_dwordx4 v[50:53], v[50:51], off
	s_nop 0
	global_load_dwordx4 v[54:57], v[54:55], off
	s_nop 0
	global_load_dwordx4 v[58:61], v[58:59], off
	s_nop 0
	global_load_dwordx4 v[62:65], v[62:63], off
	s_waitcnt lgkmcnt(0)
	v_max_f32_e32 v68, v68, v68
	v_max_f32_e32 v66, v66, v68
	ds_bpermute_b32 v68, v223, v66
	ds_bpermute_b32 v77, v199, v69
	s_waitcnt lgkmcnt(0)
	s_barrier
; #define LAS __attribute__((address_space(3)))
; __device__ __forceinline__ void attn_unit(const AttnP& P, LAS unsigned char* lds, int b, int hd, int qq, int wave, int lane) {
;     ...
;     { const float mq = wave_max(fabsf(P.gq[lane])), mk = wave_max(fabsf(P.gk[lane])); shift = fminf(8.0f * mq * mk * 1.4426950408889634f, 64.0f); shift = shift > 30.0f ? shift : 0.f; }
;     {
;         u32x4 kr[8], vr[8];
; #pragma unroll
;         for (int j = 0; j < 8; ++j) { const int chunk = tid + 512 * j, row = chunk >> 3, piece = chunk & 7, cls = row >> 5, il = row & 31;
;             kr[j] = *(const u32x4*)(P.K + ((size_t)(hb * 16 + cls) * 128 + 32 * qq + il) * 64 + piece * 8); }
; #pragma unroll
;         for (int j = 0; j < 8; ++j) { const int chunk = tid + 512 * j, cls = chunk >> 8, within = chunk & 255;
;             vr[j] = *(const u32x4*)(P.Vt + ((size_t)(hb * 16 + cls) * 16 + 4 * qq) * 512 + within * 8); }
;         __syncthreads();
; #pragma unroll
;         for (int j = 0; j < 8; ++j) { const int chunk = tid + 512 * j, row = chunk >> 3, piece = chunk & 7;
;             *(LAS u32x4*)(lds + LDS_KC + row * KC_PITCH + piece * 16) = kr[j]; }
; #pragma unroll
;         for (int j = 0; j < 8; ++j) { const int chunk = tid + 512 * j; *(LAS u32x4*)(lds + LDS_VC + chunk * 16) = vr[j]; }
;     }
;     __syncthreads();
	v_max_f32_e32 v68, v68, v68
	v_max_f32_e32 v66, v66, v68
	ds_bpermute_b32 v68, v199, v66
	v_max_f32_e32 v77, v77, v77
	v_max_f32_e32 v69, v69, v77
	v_cndmask_b32_e32 v77, v215, v221, vcc
	v_lshlrev_b32_e32 v226, 2, v77
	ds_bpermute_b32 v77, v226, v69
	s_waitcnt lgkmcnt(1)
	v_max_f32_e32 v68, v68, v68
	v_max_f32_e32 v66, v66, v68
	ds_bpermute_b32 v68, v226, v66
	v_cmp_lt_i32_e32 vcc, v222, v216
	s_waitcnt lgkmcnt(1)
	v_max_f32_e32 v77, v77, v77
	v_max_f32_e32 v69, v69, v77
	v_cndmask_b32_e32 v77, v215, v222, vcc
	v_lshlrev_b32_e32 v227, 2, v77
	s_waitcnt lgkmcnt(0)
	v_max_f32_e32 v68, v68, v68
	ds_bpermute_b32 v77, v227, v69
	v_max_f32_e32 v66, v66, v68
	ds_bpermute_b32 v68, v227, v66
	s_add_i32 s58, s99, s92
	s_lshl_b64 s[6:7], s[58:59], 7
	s_waitcnt lgkmcnt(1)
	v_max_f32_e32 v77, v77, v77
	v_max_f32_e32 v69, v69, v77
	s_waitcnt lgkmcnt(0)
	v_max_f32_e32 v68, v68, v68
	v_max_f32_e32 v66, v66, v68
	v_mul_f32_e32 v68, 0x41000000, v69
	v_mul_f32_e32 v66, v68, v66
	v_mul_f32_e32 v77, 0x3fb8aa3b, v66
	v_add_u32_e32 v66, 0, v190
	v_mad_u64_u32 v[68:69], s[4:5], v1, s71, v[66:67]
	v_lshrrev_b32_e32 v1, 3, v70
	s_waitcnt vmcnt(15)
	ds_write_b128 v68, v[2:5]
	v_mad_u64_u32 v[2:3], s[4:5], v1, s71, v[66:67]
	v_lshrrev_b32_e32 v1, 3, v71
	s_waitcnt vmcnt(14)
	ds_write_b128 v2, v[6:9]
	v_mad_u64_u32 v[2:3], s[4:5], v1, s71, v[66:67]
	v_lshrrev_b32_e32 v1, 3, v72
	s_waitcnt vmcnt(13)
	ds_write_b128 v2, v[10:13]
	v_mad_u64_u32 v[2:3], s[4:5], v1, s71, v[66:67]
	v_lshrrev_b32_e32 v1, 3, v73
	s_waitcnt vmcnt(12)
	ds_write_b128 v2, v[14:17]
	v_mad_u64_u32 v[2:3], s[4:5], v1, s71, v[66:67]
	v_lshrrev_b32_e32 v1, 3, v74
	s_waitcnt vmcnt(11)
	ds_write_b128 v2, v[18:21]
	v_mad_u64_u32 v[2:3], s[4:5], v1, s71, v[66:67]
	v_lshrrev_b32_e32 v1, 3, v75
	s_waitcnt vmcnt(10)
	ds_write_b128 v2, v[22:25]
	v_mad_u64_u32 v[2:3], s[4:5], v1, s71, v[66:67]
	v_lshrrev_b32_e32 v1, 3, v76
	s_lshl_b32 s13, s1, 5
	v_mov_b32_e32 v5, s7
	s_add_i32 s14, s12, 1
	s_lshl_b32 s19, s1, 2
	s_lshl_b32 s1, s14, 5
	s_or_b32 s22, s1, 0xffffff80
	s_lshl_b32 s20, s0, 8
	v_mov_b64_e32 v[156:157], v[84:85]
	s_add_i32 s21, s19, -4
	v_mov_b64_e32 v[154:155], v[82:83]
	s_waitcnt vmcnt(9)
	ds_write_b128 v2, v[26:29]
	v_mad_u64_u32 v[2:3], s[4:5], v1, s71, v[66:67]
	v_add_u32_e32 v1, s93, v67
	s_waitcnt vmcnt(8)
	ds_write_b128 v2, v[30:33]
	s_waitcnt vmcnt(7)
	ds_write_b128 v1, v[34:37]
	s_waitcnt vmcnt(6)
	ds_write_b128 v1, v[38:41] offset:8192
	s_waitcnt vmcnt(5)
	ds_write_b128 v1, v[42:45] offset:16384
	s_waitcnt vmcnt(4)
	ds_write_b128 v1, v[46:49] offset:24576
	s_waitcnt vmcnt(3)
	ds_write_b128 v1, v[50:53] offset:32768
	s_waitcnt vmcnt(2)
	ds_write_b128 v1, v[54:57] offset:40960
	s_waitcnt vmcnt(1)
	ds_write_b128 v1, v[58:61] offset:49152
	s_waitcnt vmcnt(0)
	ds_write_b128 v1, v[62:65] offset:57344
	v_min_f32_e32 v1, 0x42800000, v77
	v_cmp_lt_f32_e32 vcc, s30, v1
	s_waitcnt lgkmcnt(0)
	s_barrier
; #define LAS __attribute__((address_space(3)))
; __device__ __forceinline__ int next_tile(int tt, int R0) { while (tt < 26 && !tile_valid(tt, R0)) ++tt; return tt; }
; __device__ __forceinline__ void attn_task(const AttnP& P, LAS unsigned char* lds, int b, int hd, int qq, int c, float shift, int lane_in) {
;     int lane = lane_in; asm volatile("" : "+v"(lane));
;     const int hb = b * 8 + hd, q = lane & 31, h = lane >> 5, R0 = 4 * qq, iq0 = 32 * qq;
;     bf16x8 qf[4];
;     { const bf16_t* qp = P.Q + ((size_t)(hb * 16 + c) * 128 + iq0 + q) * 64 + 8 * h;
; #pragma unroll
;       for (int kk = 0; kk < 4; ++kk) qf[kk] = *(const bf16x8*)(qp + 16 * kk); }
;     bf16x8 gk[4];
;     int gi = next_tile(0, R0);
;     if (gi < 10) attn_load_k(P, lds, hb, gi, c, R0, lane, gk);
;     unsigned long long Hp[2], Hn[2], Bp[2], Bn[2], mT0[2], mT3[2], mAp[2], mAn[2], mLp, mLn;
;     { const LAS unsigned long long* T = (const LAS unsigned long long*)(lds + LDS_ATAB + lane * 144);
;       Hp[0] = T[0]; Hp[1] = T[1]; Hn[0] = T[2]; Hn[1] = T[3]; Bp[0] = T[4]; Bp[1] = T[5]; Bn[0] = T[6]; Bn[1] = T[7];
;       mT0[0] = T[8]; mT0[1] = T[9]; mT3[0] = T[10]; mT3[1] = T[11]; mAp[0] = T[12]; mAp[1] = T[13]; mAn[0] = T[14]; mAn[1] = T[15]; mLp = T[16]; mLn = T[17]; }
;     f32x16 o0 = {}, o1 = {}, zacc = {};
;     bf16x8 ones = {0x3F80, 0x3F80, 0x3F80, 0x3F80, 0x3F80, 0x3F80, 0x3F80, 0x3F80}; asm volatile("" : "+v"(ones));
;     int li = 10, ph = 0;
; __device__ __forceinline__ void attn_unit(const AttnP& P, LAS unsigned char* lds, int b, int hd, int qq, int wave, int lane) {
;     ...
;     { const float mq = wave_max(fabsf(P.gq[lane])), mk = wave_max(fabsf(P.gk[lane])); shift = fminf(8.0f * mq * mk * 1.4426950408889634f, 64.0f); shift = shift > 30.0f ? shift : 0.f; }
	v_cndmask_b32_e32 v2, 0, v1, vcc
	s_nop 0
	v_readfirstlane_b32 s100, v2
	s_nop 1
	v_cmp_class_f32_e64 s[100:101], s100, 64
	v_and_b32_e32 v229, 31, v228
	v_ashrrev_i32_e32 v17, 5, v228
	v_or_b32_e32 v1, s6, v229
	v_or_b32_e32 v4, s13, v1
	v_lshlrev_b32_e32 v6, 3, v17
	v_lshlrev_b64 v[4:5], 7, v[4:5]
	v_ashrrev_i32_e32 v7, 31, v6
	v_lshl_add_u64 v[4:5], s[46:47], 0, v[4:5]
	v_lshlrev_b64 v[6:7], 1, v[6:7]
	v_lshl_add_u64 v[4:5], v[4:5], 0, v[6:7]
	v_lshrrev_b32_e32 v1, 3, v228
	v_bfe_u32 v3, v228, 2, 1
	global_load_dwordx4 v[86:89], v[4:5], off
	global_load_dwordx4 v[90:93], v[4:5], off offset:32
	global_load_dwordx4 v[94:97], v[4:5], off offset:64
	global_load_dwordx4 v[98:101], v[4:5], off offset:96
	v_and_or_b32 v1, v1, 2, v3
	v_lshrrev_b32_e32 v3, 1, v228
	v_and_b32_e32 v4, 3, v228
	v_and_or_b32 v198, v3, 4, v4
	v_or_b32_e32 v3, s19, v1
	v_lshl_add_u32 v4, v3, 3, s22
	v_ashrrev_i32_e32 v5, 31, v4
	v_lshl_add_u64 v[4:5], s[6:7], 0, v[4:5]
	v_or_b32_e32 v4, v4, v198
	v_lshlrev_b64 v[4:5], 7, v[4:5]
	v_lshl_add_u64 v[4:5], s[50:51], 0, v[4:5]
	v_lshl_add_u64 v[4:5], v[4:5], 0, v[6:7]
	global_load_dwordx4 v[110:113], v[4:5], off
	global_load_dwordx4 v[126:129], v[4:5], off offset:32
	global_load_dwordx4 v[130:133], v[4:5], off offset:64
	global_load_dwordx4 v[106:109], v[4:5], off offset:96
	v_mul_lo_u32 v4, v228, s31
	v_add_u32_e32 v4, 0, v4
	v_add_u32_e32 v4, 0x24000, v4
	ds_read_b128 v[102:105], v4
	ds_read_b128 v[114:117], v4 offset:16
	ds_read_b128 v[118:121], v4 offset:32
	ds_read_b128 v[122:125], v4 offset:48
	ds_read_b128 v[134:137], v4 offset:64
	ds_read_b128 v[138:141], v4 offset:80
	ds_read_b128 v[142:145], v4 offset:96
	ds_read_b128 v[146:149], v4 offset:112
	ds_read_b128 v[150:153], v4 offset:128
	s_waitcnt lgkmcnt(8)
	v_mad_u64_u32 v[4:5], s[0:1], v102, 3, 0
	v_mov_b32_e32 v8, v5
	v_mad_u64_u32 v[8:9], s[0:1], v103, 3, v[8:9]
	s_waitcnt lgkmcnt(7)
	v_sub_co_u32_e32 v4, vcc, v4, v114
	v_lshlrev_b32_e32 v10, 3, v1
	s_nop 0
	v_subb_co_u32_e32 v5, vcc, v8, v115, vcc
	s_waitcnt lgkmcnt(5)
	v_lshl_add_u64 v[202:203], v[4:5], 0, v[122:123]
	v_mad_u64_u32 v[4:5], s[0:1], v104, 3, 0
	v_mov_b32_e32 v8, v5
	v_mad_u64_u32 v[8:9], s[0:1], v105, 3, v[8:9]
	v_sub_co_u32_e32 v4, vcc, v4, v116
	v_lshlrev_b32_e32 v190, 4, v229
	v_add_u32_e32 v235, 2, v17
	v_subb_co_u32_e32 v5, vcc, v8, v117, vcc
	v_lshl_add_u32 v200, v17, 4, 0
	v_or_b32_e32 v230, 0xffffffe4, v1
	s_add_i32 s15, s19, -1
	v_or_b32_e32 v231, s21, v1
	v_or_b32_e32 v232, -16, v3
	v_add_u32_e32 v233, s93, v190
	s_or_b32 s16, s19, -16
	v_add_u32_e32 v234, s21, v17
	v_add_u32_e32 v236, s21, v235
	v_lshl_add_u64 v[204:205], v[4:5], 0, v[124:125]
	v_subrev_u32_e32 v237, 26, v17
	v_lshl_add_u32 v238, v17, 10, v214
	v_lshl_add_u64 v[206:207], s[50:51], 0, v[6:7]
	v_lshl_add_u64 v[208:209], s[52:53], 0, v[190:191]
	v_or3_b32 v239, v198, v10, s36
	s_sub_i32 s17, 16, s19
	v_mov_b32_e32 v1, v2
	v_mov_b32_e32 v4, v2
	v_mov_b32_e32 v3, v2
	v_mov_b32_e32 v6, v2
	s_mov_b64 s[0:1], -1
	s_mov_b32 s23, s14
	s_mov_b32 s24, 10
	s_mov_b32 s10, 0
	v_mov_b32_e32 v18, v191
	v_mov_b32_e32 v19, v191
	v_mov_b32_e32 v20, v191
	v_mov_b32_e32 v21, v191
	v_mov_b32_e32 v22, v191
	v_mov_b32_e32 v23, v191
	v_mov_b32_e32 v24, v191
	v_mov_b32_e32 v25, v191
	v_mov_b32_e32 v26, v191
	v_mov_b32_e32 v27, v191
	v_mov_b32_e32 v28, v191
	v_mov_b32_e32 v29, v191
	v_mov_b32_e32 v30, v191
	v_mov_b32_e32 v31, v191
	v_mov_b32_e32 v32, v191
	v_mov_b32_e32 v33, v191
	v_mov_b32_e32 v34, v191
	v_mov_b32_e32 v35, v191
	v_mov_b32_e32 v36, v191
	v_mov_b32_e32 v37, v191
	v_mov_b32_e32 v38, v191
	v_mov_b32_e32 v39, v191
	v_mov_b32_e32 v40, v191
	v_mov_b32_e32 v41, v191
	v_mov_b32_e32 v42, v191
	v_mov_b32_e32 v43, v191
	v_mov_b32_e32 v44, v191
	v_mov_b32_e32 v45, v191
	v_mov_b32_e32 v46, v191
	v_mov_b32_e32 v47, v191
	v_mov_b32_e32 v48, v191
	v_mov_b32_e32 v49, v191
	v_mov_b32_e32 v50, v191
	v_mov_b32_e32 v51, v191
	v_mov_b32_e32 v52, v191
	v_mov_b32_e32 v53, v191
	v_mov_b32_e32 v54, v191
	v_mov_b32_e32 v55, v191
	v_mov_b32_e32 v56, v191
	v_mov_b32_e32 v57, v191
	v_mov_b32_e32 v58, v191
	v_mov_b32_e32 v59, v191
	v_mov_b32_e32 v60, v191
	v_mov_b32_e32 v61, v191
	v_mov_b32_e32 v62, v191
	v_mov_b32_e32 v63, v191
	v_mov_b32_e32 v64, v191
	v_mov_b32_e32 v65, v191
	v_mov_b32_e32 v5, v2
	v_mov_b32_e32 v8, v2
	v_mov_b32_e32 v7, v2
	v_mov_b32_e32 v10, v2
	v_mov_b32_e32 v9, v2
	v_mov_b32_e32 v12, v2
	v_mov_b32_e32 v11, v2
	v_mov_b32_e32 v14, v2
	v_mov_b32_e32 v13, v2
	v_mov_b32_e32 v16, v2
	v_mov_b32_e32 v15, v2
	s_waitcnt vmcnt(4)
	v_mul_lo_u32 v245, v239, s71
	v_add_u32_e32 v245, v245, v200
	s_branch .LBB0_171

; #define LAS __attribute__((address_space(3)))
; __device__ __forceinline__ void attn_load_k(const AttnP& P, LAS unsigned char* lds, int hb, int tt, int c, int R0, int lane, bf16x8 (&kf)[4]) {
;     ...
;     } else {
;         const LAS unsigned char* kp = lds + LDS_KC + ((tt - 10) * 32 + 8 * gk_ + pk_) * KC_PITCH + 16 * h;
; #pragma unroll
;         for (int kk = 0; kk < 4; ++kk) kf[kk] = *(const LAS bf16x8*)(kp + 32 * kk);
.LBB0_173:
	s_andn2_b64 vcc, exec, s[4:5]
	s_cbranch_vccnz .LBB0_178
	s_cmp_gt_i32 s24, 9
	s_cselect_b64 s[0:1], -1, 0
	s_mov_b64 s[4:5], -1
	s_and_b64 vcc, exec, s[0:1]
	s_cbranch_vccz .LBB0_214
	s_mul_i32 s4, s24, 0x1400
	v_add_u32_e32 v70, s4, v245
	ds_read_b128 v[66:69], v70
	ds_read_b128 v[178:181], v70 offset:32
	ds_read_b128 v[174:177], v70 offset:64
	ds_read_b128 v[182:185], v70 offset:96
	s_cbranch_execz .LBB0_215

; __device__ __forceinline__ void run_desc(int tt, int g, int c, int R0, int& cg, int& Rg) {
;     if (tt < 4) { cg = c; Rg = R0 - 16 + 4 * tt + g; }
;     else if (tt < 7) { cg = (c + 4 * (tt - 3)) & 15; Rg = R0 - 4 + g; }
;     else if (tt < 10) { const int o = 4 * (tt - 7) + g; const int o3 = (o * 11) >> 5; cg = (c + 1 + o3 * 4 + (o - 3 * o3)) & 15; Rg = R0 - 1; }
;     else { cg = tt - 10; Rg = R0 + g; }
; __device__ __forceinline__ void attn_load_v(const AttnP& P, LAS unsigned char* lds, int hb, int tt, int c, int R0, int lane, bf16x8 (&vf)[2][2]) {
;     ...
;         for (int s = 0; s < 2; ++s) { int cg, Rg; run_desc(tt, 2 * s + h, c, R0, cg, Rg);
;             const bf16_t* vp = P.Vt + ((size_t)((hb * 16 + cg) * 16 + Rg) * 64 + rho) * 8;
.LBB0_178:
	s_and_b64 vcc, exec, s[0:1]
	s_cbranch_vccz .LBB0_244
	s_cmp_gt_i32 s23, 3
	s_cselect_b64 s[8:9], -1, 0
	s_lshl_b32 s25, s23, 2
	s_sub_i32 s27, s25, 28
	s_cmp_gt_u32 s23, 6
	s_cselect_b64 s[0:1], -1, 0
	s_add_i32 s4, s25, s63
	s_waitcnt lgkmcnt(3)
	v_cndmask_b32_e64 v66, 0, 1, s[0:1]
	s_and_b32 s26, s4, 15
	s_mov_b64 s[10:11], -1
	s_and_b64 vcc, exec, s[8:9]
	v_cmp_ne_u32_e64 s[4:5], 1, v66
	s_cbranch_vccz .LBB0_183
	s_and_b64 vcc, exec, s[4:5]
	v_mov_b32_e32 v67, s26
	v_mov_b32_e32 v66, v234
	s_cbranch_vccnz .LBB0_182
	v_add_u32_e32 v66, s27, v17
	v_mul_u32_u24_e32 v67, 11, v66
	v_lshrrev_b32_e32 v67, 5, v67
	v_add3_u32 v66, v66, s62, v67
	v_and_b32_e32 v67, 15, v66
	v_mov_b32_e32 v66, s15

; __device__ __forceinline__ void run_desc(int tt, int g, int c, int R0, int& cg, int& Rg) {
;     if (tt < 4) { cg = c; Rg = R0 - 16 + 4 * tt + g; }
;     else if (tt < 7) { cg = (c + 4 * (tt - 3)) & 15; Rg = R0 - 4 + g; }
;     else if (tt < 10) { const int o = 4 * (tt - 7) + g; const int o3 = (o * 11) >> 5; cg = (c + 1 + o3 * 4 + (o - 3 * o3)) & 15; Rg = R0 - 1; }
;     else { cg = tt - 10; Rg = R0 + g; }
; __device__ __forceinline__ void attn_load_v(const AttnP& P, LAS unsigned char* lds, int hb, int tt, int c, int R0, int lane, bf16x8 (&vf)[2][2]) {
;     ...
;         for (int s = 0; s < 2; ++s) { int cg, Rg; run_desc(tt, 2 * s + h, c, R0, cg, Rg);
;             const bf16_t* vp = P.Vt + ((size_t)((hb * 16 + cg) * 16 + Rg) * 64 + rho) * 8;
;             vf[0][s] = *(const bf16x8*)(vp); vf[1][s] = *(const bf16x8*)(vp + 32 * 8); }
.LBB0_185:
	v_lshlrev_b32_e32 v67, 4, v67
	v_add3_u32 v66, v67, s20, v66
	v_ashrrev_i32_e32 v67, 31, v66
	v_lshlrev_b64 v[66:67], 10, v[66:67]
	v_lshl_add_u64 v[66:67], v[208:209], 0, v[66:67]
	global_load_dwordx4 v[162:165], v[66:67], off
	s_waitcnt lgkmcnt(2)
	global_load_dwordx4 v[158:161], v[66:67], off offset:512
	s_andn2_b64 vcc, exec, s[8:9]
	s_mov_b64 s[10:11], -1
	s_cbranch_vccnz .LBB0_189
	s_and_b64 vcc, exec, s[4:5]
	v_mov_b32_e32 v67, s26
	v_mov_b32_e32 v66, v236
	s_cbranch_vccnz .LBB0_188
	v_add_u32_e32 v66, s27, v235
	v_mul_u32_u24_e32 v67, 11, v66
	v_lshrrev_b32_e32 v67, 5, v67
	v_add3_u32 v66, v66, s62, v67
	v_and_b32_e32 v67, 15, v66
	v_mov_b32_e32 v66, s15

; __device__ __forceinline__ void run_desc(int tt, int g, int c, int R0, int& cg, int& Rg) {
;     if (tt < 4) { cg = c; Rg = R0 - 16 + 4 * tt + g; }
;     else if (tt < 7) { cg = (c + 4 * (tt - 3)) & 15; Rg = R0 - 4 + g; }
;     else if (tt < 10) { const int o = 4 * (tt - 7) + g; const int o3 = (o * 11) >> 5; cg = (c + 1 + o3 * 4 + (o - 3 * o3)) & 15; Rg = R0 - 1; }
;     else { cg = tt - 10; Rg = R0 + g; }
; __device__ __forceinline__ void attn_task(const AttnP& P, LAS unsigned char* lds, int b, int hd, int qq, int c, float shift, int lane_in) {
;     ...
;             } else {
;                 { int cg, Rg; run_desc(gi, h, c, R0, cg, Rg); w0 = (c > cg) ? mLp : mLn; }
;                 { int cg, Rg; run_desc(gi, 2 + h, c, R0, cg, Rg); w1 = (c > cg) ? mLp : mLn; }
.LBB0_191:
	v_lshlrev_b32_e32 v67, 4, v67
	v_add3_u32 v66, v67, s20, v66
	v_ashrrev_i32_e32 v67, 31, v66
	v_lshlrev_b64 v[66:67], 10, v[66:67]
	v_lshl_add_u64 v[66:67], v[208:209], 0, v[66:67]
	s_waitcnt lgkmcnt(1)
	global_load_dwordx4 v[166:169], v[66:67], off
	s_waitcnt lgkmcnt(0)
	global_load_dwordx4 v[170:173], v[66:67], off offset:512
	s_mov_b64 s[4:5], -1
	s_and_b64 vcc, exec, s[8:9]
	s_cbranch_vccz .LBB0_197
	s_and_b64 vcc, exec, s[0:1]
	s_cbranch_vccz .LBB0_194
	v_add_u32_e32 v66, s27, v17
	v_mul_u32_u24_e32 v67, 11, v66
	v_lshrrev_b32_e32 v67, 5, v67
	v_add3_u32 v66, v66, s62, v67
	v_and_b32_e32 v66, 15, v66
	v_cmp_gt_u32_e32 vcc, s92, v66
	v_add_u32_e32 v66, s25, v237
	v_mul_u32_u24_e32 v67, 11, v66
	v_lshrrev_b32_e32 v67, 5, v67
	v_add3_u32 v66, v66, s62, v67
	v_and_b32_e32 v66, 15, v66
	v_cndmask_b32_e32 v213, v153, v151, vcc
	v_cndmask_b32_e32 v212, v152, v150, vcc
	v_cmp_gt_u32_e32 vcc, s92, v66
	s_mov_b64 s[4:5], 0
	s_nop 0
	v_cndmask_b32_e32 v211, v153, v151, vcc
	v_cndmask_b32_e32 v210, v152, v150, vcc

; #define LAS __attribute__((address_space(3)))
; __device__ __forceinline__ int next_tile(int tt, int R0) { while (tt < 26 && !tile_valid(tt, R0)) ++tt; return tt; }
; __device__ __forceinline__ void attn_load_k(const AttnP& P, LAS unsigned char* lds, int hb, int tt, int c, int R0, int lane, bf16x8 (&kf)[4]) {
;     const int rho = lane & 31, h = lane >> 5;
;     const int gk_ = 2 * (rho >> 4) + ((rho >> 2) & 1), pk_ = 4 * ((rho >> 3) & 1) + (rho & 3);
;     if (tt < 10) {
;         int cg, Rg; run_desc(tt, gk_, c, R0, cg, Rg);
;         const bf16_t* kp = P.K + ((size_t)(hb * 16 + cg) * 128 + 8 * Rg + pk_) * 64 + 8 * h;
; #pragma unroll
;         for (int kk = 0; kk < 4; ++kk) kf[kk] = *(const bf16x8*)(kp + 16 * kk);
; __device__ __forceinline__ void attn_task(const AttnP& P, LAS unsigned char* lds, int b, int hd, int qq, int c, float shift, int lane_in) {
;     ...
;             gi = next_tile(gi + 1, R0);
;             if (gi < 10) attn_load_k(P, lds, hb, gi, c, R0, lane, gk);
.LBB0_203:
	s_add_i32 s0, s25, 4
	s_max_i32 s0, s0, s17
	s_not_b32 s1, s25
	s_add_i32 s0, s0, s1
	s_max_i32 s1, s23, 3
	s_lshr_b32 s0, s0, 2
	s_sub_i32 s1, s1, s23
	s_min_u32 s0, s0, s1
	s_add_i32 s0, s23, s0
	s_add_i32 s23, s0, 1
	s_waitcnt vmcnt(4)
	v_mov_b64_e32 v[184:185], v[108:109]
	v_mov_b64_e32 v[182:183], v[106:107]
	v_mov_b64_e32 v[176:177], v[132:133]
	v_mov_b64_e32 v[174:175], v[130:131]
	v_mov_b64_e32 v[180:181], v[128:129]
	v_mov_b64_e32 v[178:179], v[126:127]
	v_mov_b64_e32 v[68:69], v[112:113]
	v_mov_b64_e32 v[66:67], v[110:111]
	s_cmp_gt_i32 s0, 8
	s_cbranch_scc1 .Lattn_nopf_1
	s_lshl_b32 s4, s23, 2
	s_cmp_gt_i32 s0, 2
	s_mov_b64 s[0:1], -1
	s_cbranch_scc0 .LBB0_210
	s_cmp_gt_u32 s23, 6
	s_cbranch_scc0 .LBB0_207
	v_add_u32_e32 v70, s4, v230
	v_mul_u32_u24_e32 v71, 11, v70
	v_lshrrev_b32_e32 v71, 5, v71
	v_add3_u32 v70, v70, s62, v71
	v_and_b32_e32 v70, 15, v70
	s_mov_b64 s[0:1], 0

; __device__ __forceinline__ void run_desc(int tt, int g, int c, int R0, int& cg, int& Rg) {
;     if (tt < 4) { cg = c; Rg = R0 - 16 + 4 * tt + g; }
;     else if (tt < 7) { cg = (c + 4 * (tt - 3)) & 15; Rg = R0 - 4 + g; }
;     else if (tt < 10) { const int o = 4 * (tt - 7) + g; const int o3 = (o * 11) >> 5; cg = (c + 1 + o3 * 4 + (o - 3 * o3)) & 15; Rg = R0 - 1; }
;     else { cg = tt - 10; Rg = R0 + g; }
; __device__ __forceinline__ void attn_load_k(const AttnP& P, LAS unsigned char* lds, int hb, int tt, int c, int R0, int lane, bf16x8 (&kf)[4]) {
;     ...
;     if (tt < 10) {
;         int cg, Rg; run_desc(tt, gk_, c, R0, cg, Rg);
;         const bf16_t* kp = P.K + ((size_t)(hb * 16 + cg) * 128 + 8 * Rg + pk_) * 64 + 8 * h;
.LBB0_215:
	s_lshl_b32 s8, s24, 2
	s_cmp_gt_i32 s24, 3
	s_mov_b64 s[4:5], -1
	s_cbranch_scc0 .LBB0_221
	s_cmp_gt_u32 s24, 6
	s_cbranch_scc0 .LBB0_218
	s_waitcnt lgkmcnt(3)
	v_add_u32_e32 v66, s8, v230
	v_mul_u32_u24_e32 v67, 11, v66
	v_lshrrev_b32_e32 v67, 5, v67
	v_add3_u32 v66, v66, s62, v67
	v_and_b32_e32 v66, 15, v66
	s_mov_b64 s[4:5], 0

; __device__ __forceinline__ void run_desc(int tt, int g, int c, int R0, int& cg, int& Rg) {
;     if (tt < 4) { cg = c; Rg = R0 - 16 + 4 * tt + g; }
;     else if (tt < 7) { cg = (c + 4 * (tt - 3)) & 15; Rg = R0 - 4 + g; }
;     else if (tt < 10) { const int o = 4 * (tt - 7) + g; const int o3 = (o * 11) >> 5; cg = (c + 1 + o3 * 4 + (o - 3 * o3)) & 15; Rg = R0 - 1; }
;     else { cg = tt - 10; Rg = R0 + g; }
; __device__ __forceinline__ void attn_load_v(const AttnP& P, LAS unsigned char* lds, int hb, int tt, int c, int R0, int lane, bf16x8 (&vf)[2][2]) {
;     ...
;         for (int s = 0; s < 2; ++s) { int cg, Rg; run_desc(tt, 2 * s + h, c, R0, cg, Rg);
;             const bf16_t* vp = P.Vt + ((size_t)((hb * 16 + cg) * 16 + Rg) * 64 + rho) * 8;
.LBB0_225:
	s_cmp_gt_i32 s24, 3
	s_cselect_b64 s[0:1], -1, 0
	s_lshl_b32 s26, s24, 2
	s_sub_i32 s11, s26, 28
	s_cmp_gt_u32 s24, 6
	s_cselect_b64 s[4:5], -1, 0
	s_add_i32 s8, s26, s63
	v_cndmask_b32_e64 v70, 0, 1, s[4:5]
	s_and_b32 s25, s8, 15
	s_mov_b64 s[8:9], -1
	s_and_b64 vcc, exec, s[0:1]
	v_cmp_ne_u32_e64 s[4:5], 1, v70
	s_cbranch_vccz .LBB0_229
	s_and_b64 vcc, exec, s[4:5]
	v_mov_b32_e32 v71, s25
	v_mov_b32_e32 v70, v234
	s_cbranch_vccnz .LBB0_228
	v_add_u32_e32 v70, s11, v17
	v_mul_u32_u24_e32 v71, 11, v70
	v_lshrrev_b32_e32 v71, 5, v71
	v_add3_u32 v70, v70, s62, v71
	v_and_b32_e32 v71, 15, v70
	v_mov_b32_e32 v70, s15

; __device__ __forceinline__ void run_desc(int tt, int g, int c, int R0, int& cg, int& Rg) {
;     if (tt < 4) { cg = c; Rg = R0 - 16 + 4 * tt + g; }
;     else if (tt < 7) { cg = (c + 4 * (tt - 3)) & 15; Rg = R0 - 4 + g; }
;     else if (tt < 10) { const int o = 4 * (tt - 7) + g; const int o3 = (o * 11) >> 5; cg = (c + 1 + o3 * 4 + (o - 3 * o3)) & 15; Rg = R0 - 1; }
;     else { cg = tt - 10; Rg = R0 + g; }
; __device__ __forceinline__ void attn_load_v(const AttnP& P, LAS unsigned char* lds, int hb, int tt, int c, int R0, int lane, bf16x8 (&vf)[2][2]) {
;     ...
;         for (int s = 0; s < 2; ++s) { int cg, Rg; run_desc(tt, 2 * s + h, c, R0, cg, Rg);
;             const bf16_t* vp = P.Vt + ((size_t)((hb * 16 + cg) * 16 + Rg) * 64 + rho) * 8;
;             vf[0][s] = *(const bf16x8*)(vp); vf[1][s] = *(const bf16x8*)(vp + 32 * 8); }
.LBB0_231:
	v_lshlrev_b32_e32 v71, 4, v71
	v_add3_u32 v70, v71, s20, v70
	v_ashrrev_i32_e32 v71, 31, v70
	v_lshlrev_b64 v[70:71], 10, v[70:71]
	v_lshl_add_u64 v[70:71], v[208:209], 0, v[70:71]
	s_waitcnt lgkmcnt(3)
	global_load_dwordx4 v[162:165], v[70:71], off
	s_waitcnt lgkmcnt(2)
	global_load_dwordx4 v[158:161], v[70:71], off offset:512
	s_andn2_b64 vcc, exec, s[0:1]
	s_mov_b64 s[0:1], -1
	s_cbranch_vccnz .LBB0_235
	s_and_b64 vcc, exec, s[4:5]
	v_mov_b32_e32 v71, s25
	v_mov_b32_e32 v70, v236
	s_cbranch_vccnz .LBB0_234
	v_add_u32_e32 v70, s11, v235
	v_mul_u32_u24_e32 v71, 11, v70
	v_lshrrev_b32_e32 v71, 5, v71
	v_add3_u32 v70, v70, s62, v71
	v_and_b32_e32 v71, 15, v70
	v_mov_b32_e32 v70, s15

; __device__ __forceinline__ void attn_task(const AttnP& P, LAS unsigned char* lds, int b, int hd, int qq, int c, float shift, int lane_in) {
;     ...
;             const int dl = c - (li - 10);
;             if (dl == 0) { w0 = 3 * Hp[0] - Hn[0] + Bn[0]; w1 = 3 * Hp[1] - Hn[1] + Bn[1]; }
;             else if (dl > 0) { const unsigned long long m = ((dl & 3) == 0) ? ~0ull : 0ull; w0 = Bp[0] + (Hp[0] & m); w1 = Bp[1] + (Hp[1] & m); }
;             else { const unsigned long long m = ((dl & 3) == 0) ? ~0ull : 0ull; w0 = Bn[0] + (Hn[0] & m); w1 = Bn[1] + (Hn[1] & m); }
.LBB0_238:
	s_add_i32 s0, s24, -10
	s_cmp_eq_u32 s92, s0
	s_cbranch_scc1 .Latb0_own
	s_sub_i32 s4, s92, s0
	s_and_b32 s0, s4, 3
	s_cmp_lg_u32 s0, 0
	s_cbranch_scc1 .Latb0_pure
	s_cmp_lt_i32 s4, 1
	s_mov_b64 s[4:5], -1
	s_cbranch_scc0 .LBB0_241
	v_lshl_add_u64 v[212:213], v[114:115], 0, v[122:123]
	v_lshl_add_u64 v[210:211], v[116:117], 0, v[124:125]
	s_mov_b64 s[4:5], 0
.LBB0_241:
	s_andn2_b64 vcc, exec, s[4:5]
	s_cbranch_vccnz .LBB0_243
	v_lshl_add_u64 v[212:213], v[102:103], 0, v[118:119]
	v_lshl_add_u64 v[210:211], v[104:105], 0, v[120:121]
	s_branch .LBB0_243
.Latb0_own:
	v_mov_b64_e32 v[210:211], v[204:205]
	v_mov_b64_e32 v[212:213], v[202:203]
	s_branch .LBB0_243
.Latb0_pure:
	s_cmp_lt_i32 s4, 1
	s_cbranch_scc1 .Latb0_pneg
	v_mov_b64_e32 v[212:213], v[118:119]
	v_mov_b64_e32 v[210:211], v[120:121]
	s_branch .LBB0_243
.Latb0_pneg:
	v_mov_b64_e32 v[212:213], v[122:123]
	v_mov_b64_e32 v[210:211], v[124:125]

; __device__ __forceinline__ void tile_compute(const bf16x8 (&kf)[4], const bf16x8 (&vf)[2][2], const bf16x8 (&qf)[4], unsigned long long w0, unsigned long long w1,
;                                              float shift, f32x16& o0, f32x16& o1, f32x16& zacc, const bf16x8& ones) {
;     f32x16 st = {};
; #pragma unroll
;     for (int kk = 0; kk < 4; ++kk) st = __builtin_amdgcn_mfma_f32_32x32x16_bf16(kf[kk], qf[kk], st, 0, 0, 0);
;     if (__builtin_amdgcn_readfirstlane(__builtin_bit_cast(int, shift)) != 0) {
;         asm volatile("" ::: "memory");
; #pragma unroll
;         for (int e = 0; e < 16; ++e) st[e] -= shift;
;     }
.LBB0_245:
	s_waitcnt lgkmcnt(3)
	v_mfma_f32_32x32x16_bf16 v[66:81], v[66:69], v[86:89], 0
	s_and_b64 vcc, exec, s[100:101]
	s_waitcnt lgkmcnt(2)
	v_mfma_f32_32x32x16_bf16 v[66:81], v[178:181], v[90:93], v[66:81]
	s_waitcnt lgkmcnt(1)
	v_mfma_f32_32x32x16_bf16 v[66:81], v[174:177], v[94:97], v[66:81]
	s_waitcnt lgkmcnt(0)
	v_mfma_f32_32x32x16_bf16 v[66:81], v[182:185], v[98:101], v[66:81]
	s_cbranch_vccnz .LBB0_170
	s_nop 10
	v_sub_f32_e32 v81, v81, v15
	v_sub_f32_e32 v80, v80, v16
	v_sub_f32_e32 v79, v79, v13
	v_sub_f32_e32 v78, v78, v14
	v_sub_f32_e32 v77, v77, v11
	v_sub_f32_e32 v76, v76, v12
	v_sub_f32_e32 v75, v75, v9
	v_sub_f32_e32 v74, v74, v10
	v_sub_f32_e32 v73, v73, v7
	v_sub_f32_e32 v72, v72, v8
	v_sub_f32_e32 v71, v71, v5
	v_sub_f32_e32 v70, v70, v6
	v_sub_f32_e32 v69, v69, v3
	v_sub_f32_e32 v68, v68, v4
	v_sub_f32_e32 v67, v67, v1
	v_sub_f32_e32 v66, v66, v2
	s_branch .LBB0_170

; #define LAS __attribute__((address_space(3)))
; __device__ __forceinline__ unsigned pk2(float lo, float hi) { f32x2 v = {lo, hi}; bf16x2_t b = __builtin_convertvector(v, bf16x2_t); return __builtin_bit_cast(unsigned, b); }
; __device__ __forceinline__ int next_tile(int tt, int R0) { while (tt < 26 && !tile_valid(tt, R0)) ++tt; return tt; }
; __device__ __forceinline__ void attn_task(const AttnP& P, LAS unsigned char* lds, int b, int hd, int qq, int c, float shift, int lane_in) {
;     ...
;     const int hb = b * 8 + hd, q = lane & 31, h = lane >> 5, R0 = 4 * qq, iq0 = 32 * qq;
;     bf16x8 qf[4];
;     { const bf16_t* qp = P.Q + ((size_t)(hb * 16 + c) * 128 + iq0 + q) * 64 + 8 * h;
; #pragma unroll
;       for (int kk = 0; kk < 4; ++kk) qf[kk] = *(const bf16x8*)(qp + 16 * kk); }
;     bf16x8 gk[4];
;     int gi = next_tile(0, R0);
;     if (gi < 10) attn_load_k(P, lds, hb, gi, c, R0, lane, gk);
;     unsigned long long Hp[2], Hn[2], Bp[2], Bn[2], mT0[2], mT3[2], mAp[2], mAn[2], mLp, mLn;
;     { const LAS unsigned long long* T = (const LAS unsigned long long*)(lds + LDS_ATAB + lane * 144);
;       Hp[0] = T[0]; Hp[1] = T[1]; Hn[0] = T[2]; Hn[1] = T[3]; Bp[0] = T[4]; Bp[1] = T[5]; Bn[0] = T[6]; Bn[1] = T[7];
;       mT0[0] = T[8]; mT0[1] = T[9]; mT3[0] = T[10]; mT3[1] = T[11]; mAp[0] = T[12]; mAp[1] = T[13]; mAn[0] = T[14]; mAn[1] = T[15]; mLp = T[16]; mLn = T[17]; }
;     f32x16 o0 = {}, o1 = {}, zacc = {};
;     bf16x8 ones = {0x3F80, 0x3F80, 0x3F80, 0x3F80, 0x3F80, 0x3F80, 0x3F80, 0x3F80}; asm volatile("" : "+v"(ones));
;     int li = 10, ph = 0;
;     ...
;     const float rz = __builtin_amdgcn_rcpf(zacc[0]);
;     float ss = 0.f;
; #pragma unroll
;     for (int e = 0; e < 16; ++e) { o0[e] *= rz; o1[e] *= rz; ss += o0[e] * o0[e] + o1[e] * o1[e]; }
;     ss = xor32_sum(ss);
;     const size_t tok = (size_t)b * SEQ + c + 16 * (iq0 + q);
;     if (h == 0) P.ssqA[tok * 8 + hd] = ss;
;     bf16_t* orow = P.MIX + tok * DM + hd * 64;
; #pragma unroll
;     for (int e4 = 0; e4 < 4; ++e4) {
;         const int d0 = 8 * e4 + 4 * h;
;         u32x2 w0, w1;
;         w0.x = pk2(o0[4 * e4], o0[4 * e4 + 1]); w0.y = pk2(o0[4 * e4 + 2], o0[4 * e4 + 3]);
;         w1.x = pk2(o1[4 * e4], o1[4 * e4 + 1]); w1.y = pk2(o1[4 * e4 + 2], o1[4 * e4 + 3]);
;         *(u32x2*)(orow + d0) = w0; *(u32x2*)(orow + 32 + d0) = w1;
;     }
.LBB0_249:
	s_or_b64 exec, exec, s[0:1]
	v_readlane_b32 s0, v243, 20
	v_lshlrev_b64 v[48:49], 11, v[190:191]
	v_readlane_b32 s1, v243, 21
	s_lshl_b32 s58, s98, 7
	v_lshlrev_b32_e32 v52, 2, v17
	v_lshl_add_u64 v[48:49], s[0:1], 0, v[48:49]
	v_lshl_add_u64 v[48:49], v[48:49], 0, s[58:59]
	v_ashrrev_i32_e32 v53, 31, v52
	v_cvt_pk_bf16_f32 v50, v50, v51
	v_cvt_pk_bf16_f32 v51, v34, v35
	v_cvt_pk_bf16_f32 v18, v18, v19
	v_cvt_pk_bf16_f32 v19, v20, v21
	v_lshl_add_u64 v[20:21], v[52:53], 1, v[48:49]
	v_bfe_u32 v144, v0, 5, 1
	v_lshlrev_b32_e32 v144, 3, v144
	v_mov_b32_e32 v145, 0
	v_lshl_add_u64 v[146:147], v[20:21], 0, v[144:145]
	v_mov_b32_e32 v128, v50
	v_mov_b32_e32 v129, v51
	v_mov_b32_e32 v136, v18
	v_mov_b32_e32 v137, v19
	v_cvt_pk_bf16_f32 v18, v36, v37
	v_cvt_pk_bf16_f32 v19, v38, v39
	v_cvt_pk_bf16_f32 v22, v22, v23
	v_cvt_pk_bf16_f32 v23, v24, v25
	v_mov_b32_e32 v130, v18
	v_mov_b32_e32 v131, v19
	s_nop 1
	v_permlane32_swap_b32_e32 v128, v130
	v_permlane32_swap_b32_e32 v129, v131
	global_store_dwordx4 v[146:147], v[128:131], off
	v_mov_b32_e32 v138, v22
	v_mov_b32_e32 v139, v23
	s_nop 1
	v_permlane32_swap_b32_e32 v136, v138
	v_permlane32_swap_b32_e32 v137, v139
	global_store_dwordx4 v[146:147], v[136:139], off offset:64
	v_cvt_pk_bf16_f32 v18, v40, v41
	v_cvt_pk_bf16_f32 v19, v42, v43
	v_cvt_pk_bf16_f32 v22, v26, v27
	v_cvt_pk_bf16_f32 v23, v28, v29
	v_mov_b32_e32 v132, v18
	v_mov_b32_e32 v133, v19
	v_mov_b32_e32 v140, v22
	v_mov_b32_e32 v141, v23
	v_cvt_pk_bf16_f32 v18, v44, v45
	v_cvt_pk_bf16_f32 v19, v46, v47
	v_mov_b32_e32 v229, v201
	s_add_i32 s58, s99, s64
	v_cvt_pk_bf16_f32 v22, v30, v31
	v_cvt_pk_bf16_f32 v23, v32, v33
	v_mov_b32_e32 v134, v18
	v_mov_b32_e32 v135, v19
	s_nop 1
	v_permlane32_swap_b32_e32 v132, v134
	v_permlane32_swap_b32_e32 v133, v135
	global_store_dwordx4 v[146:147], v[132:135], off offset:32
	v_mov_b32_e32 v142, v22
	v_mov_b32_e32 v143, v23
	s_nop 1
	v_permlane32_swap_b32_e32 v140, v142
	v_permlane32_swap_b32_e32 v141, v143
	global_store_dwordx4 v[146:147], v[140:143], off offset:96
	s_lshl_b64 s[26:27], s[58:59], 7
	v_and_b32_e32 v230, 31, v229
	v_ashrrev_i32_e32 v228, 5, v229
	v_or_b32_e32 v17, s26, v230
	v_mov_b32_e32 v19, s27
	v_or_b32_e32 v18, s13, v17
	v_lshlrev_b32_e32 v20, 3, v228
	v_lshlrev_b64 v[18:19], 7, v[18:19]
	v_ashrrev_i32_e32 v21, 31, v20
	v_lshl_add_u64 v[18:19], s[46:47], 0, v[18:19]
	v_lshlrev_b64 v[20:21], 1, v[20:21]
	v_lshl_add_u64 v[18:19], v[18:19], 0, v[20:21]
	global_load_dwordx4 v[86:89], v[18:19], off
	global_load_dwordx4 v[90:93], v[18:19], off offset:32
	global_load_dwordx4 v[94:97], v[18:19], off offset:64
	global_load_dwordx4 v[98:101], v[18:19], off offset:96
	v_lshrrev_b32_e32 v17, 3, v229
	v_bfe_u32 v18, v229, 2, 1
	v_and_or_b32 v22, v17, 2, v18
	v_lshrrev_b32_e32 v17, 1, v229
	v_and_b32_e32 v18, 3, v229
	v_or_b32_e32 v23, s19, v22
	v_and_or_b32 v198, v17, 4, v18
	v_lshl_add_u32 v18, v23, 3, s22
	v_ashrrev_i32_e32 v19, 31, v18
	v_lshl_add_u64 v[18:19], s[26:27], 0, v[18:19]
	v_or_b32_e32 v18, v18, v198
	v_lshlrev_b64 v[18:19], 7, v[18:19]
	v_lshl_add_u64 v[18:19], s[50:51], 0, v[18:19]
	v_lshl_add_u64 v[18:19], v[18:19], 0, v[20:21]
	global_load_dwordx4 v[110:113], v[18:19], off
	global_load_dwordx4 v[126:129], v[18:19], off offset:32
	global_load_dwordx4 v[130:133], v[18:19], off offset:64
	global_load_dwordx4 v[106:109], v[18:19], off offset:96
	v_mul_lo_u32 v17, v229, s31
	v_add_u32_e32 v17, 0, v17
	v_add_u32_e32 v17, 0x24000, v17
	ds_read_b128 v[102:105], v17
	ds_read_b128 v[114:117], v17 offset:16
	ds_read_b128 v[118:121], v17 offset:32
	ds_read_b128 v[122:125], v17 offset:48
	ds_read_b128 v[134:137], v17 offset:64
	ds_read_b128 v[138:141], v17 offset:80
	ds_read_b128 v[142:145], v17 offset:96
	ds_read_b128 v[146:149], v17 offset:112
	ds_read_b128 v[150:153], v17 offset:128
	s_waitcnt lgkmcnt(8)
	v_mad_u64_u32 v[18:19], s[0:1], v102, 3, 0
	v_lshlrev_b32_e32 v24, 3, v22
	v_or_b32_e32 v17, 0xffffffe4, v22
	v_or_b32_e32 v231, s21, v22
	v_mov_b32_e32 v22, v19
	v_or_b32_e32 v232, -16, v23
	v_mad_u64_u32 v[22:23], s[0:1], v103, 3, v[22:23]
	s_waitcnt lgkmcnt(7)
	v_sub_co_u32_e32 v18, vcc, v18, v114
	v_mov_b64_e32 v[156:157], v[84:85]
	s_nop 0
	v_subb_co_u32_e32 v19, vcc, v22, v115, vcc
	s_waitcnt lgkmcnt(5)
	v_lshl_add_u64 v[202:203], v[18:19], 0, v[122:123]
	v_mad_u64_u32 v[18:19], s[0:1], v104, 3, 0
	v_mov_b32_e32 v22, v19
	v_mad_u64_u32 v[22:23], s[0:1], v105, 3, v[22:23]
	v_sub_co_u32_e32 v18, vcc, v18, v116
	v_lshlrev_b32_e32 v190, 4, v230
	s_nop 0
	v_subb_co_u32_e32 v19, vcc, v22, v117, vcc
	v_add_u32_e32 v235, 2, v228
	v_lshl_add_u64 v[204:205], v[18:19], 0, v[124:125]
	v_mov_b32_e32 v18, 0
	s_lshl_b32 s23, s98, 6
	v_mov_b64_e32 v[154:155], v[82:83]
	v_lshl_add_u32 v200, v228, 4, 0
	v_add_u32_e32 v233, s93, v190
	v_add_u32_e32 v234, s21, v228
	v_add_u32_e32 v236, s21, v235
	v_subrev_u32_e32 v237, 26, v228
	s_mov_b32 s19, 10
	v_lshl_add_u32 v238, v228, 10, v214
	v_lshl_add_u64 v[206:207], s[50:51], 0, v[20:21]
	v_lshl_add_u64 v[208:209], s[52:53], 0, v[190:191]
	v_or3_b32 v239, v198, v24, s36
	s_mov_b32 s10, 0
	s_mov_b64 s[0:1], -1
	v_mov_b32_e32 v19, v18
	v_mov_b32_e32 v20, v18
	v_mov_b32_e32 v21, v18
	v_mov_b32_e32 v22, v18
	v_mov_b32_e32 v23, v18
	v_mov_b32_e32 v24, v18
	v_mov_b32_e32 v25, v18
	v_mov_b32_e32 v26, v18
	v_mov_b32_e32 v27, v18
	v_mov_b32_e32 v28, v18
	v_mov_b32_e32 v29, v18
	v_mov_b32_e32 v30, v18
	v_mov_b32_e32 v31, v18
	v_mov_b32_e32 v32, v18
	v_mov_b32_e32 v33, v18
	v_mov_b32_e32 v34, v18
	v_mov_b32_e32 v35, v18
	v_mov_b32_e32 v36, v18
	v_mov_b32_e32 v37, v18
	v_mov_b32_e32 v38, v18
	v_mov_b32_e32 v39, v18
	v_mov_b32_e32 v40, v18
	v_mov_b32_e32 v41, v18
	v_mov_b32_e32 v42, v18
	v_mov_b32_e32 v43, v18
	v_mov_b32_e32 v44, v18
	v_mov_b32_e32 v45, v18
	v_mov_b32_e32 v46, v18
	v_mov_b32_e32 v47, v18
	v_mov_b32_e32 v48, v18
	v_mov_b32_e32 v49, v18
	v_mov_b32_e32 v50, v18
	v_mov_b32_e32 v51, v18
	v_mov_b32_e32 v52, v18
	v_mov_b32_e32 v53, v18
	v_mov_b32_e32 v54, v18
	v_mov_b32_e32 v55, v18
	v_mov_b32_e32 v56, v18
	v_mov_b32_e32 v57, v18
	v_mov_b32_e32 v58, v18
	v_mov_b32_e32 v59, v18
	v_mov_b32_e32 v60, v18
	v_mov_b32_e32 v61, v18
	v_mov_b32_e32 v62, v18
	v_mov_b32_e32 v63, v18
	v_mov_b32_e32 v64, v18
	v_mov_b32_e32 v65, v18
	s_waitcnt vmcnt(4)
	v_mul_lo_u32 v245, v239, s71
	v_add_u32_e32 v245, v245, v200
	s_branch .LBB0_251

; #define LAS __attribute__((address_space(3)))
; __device__ __forceinline__ void attn_load_k(const AttnP& P, LAS unsigned char* lds, int hb, int tt, int c, int R0, int lane, bf16x8 (&kf)[4]) {
;     ...
;     } else {
;         const LAS unsigned char* kp = lds + LDS_KC + ((tt - 10) * 32 + 8 * gk_ + pk_) * KC_PITCH + 16 * h;
; #pragma unroll
;         for (int kk = 0; kk < 4; ++kk) kf[kk] = *(const LAS bf16x8*)(kp + 32 * kk);
.LBB0_253:
	s_andn2_b64 vcc, exec, s[4:5]
	s_cbranch_vccnz .LBB0_258
	s_cmp_gt_i32 s19, 9
	s_cselect_b64 s[0:1], -1, 0
	s_mov_b64 s[4:5], -1
	s_and_b64 vcc, exec, s[0:1]
	s_cbranch_vccz .LBB0_294
	s_mul_i32 s4, s19, 0x1400
	v_add_u32_e32 v70, s4, v245
	ds_read_b128 v[66:69], v70
	ds_read_b128 v[178:181], v70 offset:32
	ds_read_b128 v[174:177], v70 offset:64
	ds_read_b128 v[182:185], v70 offset:96
	s_cbranch_execz .LBB0_295

; __device__ __forceinline__ void run_desc(int tt, int g, int c, int R0, int& cg, int& Rg) {
;     if (tt < 4) { cg = c; Rg = R0 - 16 + 4 * tt + g; }
;     else if (tt < 7) { cg = (c + 4 * (tt - 3)) & 15; Rg = R0 - 4 + g; }
;     else if (tt < 10) { const int o = 4 * (tt - 7) + g; const int o3 = (o * 11) >> 5; cg = (c + 1 + o3 * 4 + (o - 3 * o3)) & 15; Rg = R0 - 1; }
;     else { cg = tt - 10; Rg = R0 + g; }
; __device__ __forceinline__ void attn_load_v(const AttnP& P, LAS unsigned char* lds, int hb, int tt, int c, int R0, int lane, bf16x8 (&vf)[2][2]) {
;     ...
;         for (int s = 0; s < 2; ++s) { int cg, Rg; run_desc(tt, 2 * s + h, c, R0, cg, Rg);
;             const bf16_t* vp = P.Vt + ((size_t)((hb * 16 + cg) * 16 + Rg) * 64 + rho) * 8;
.LBB0_258:
	s_and_b64 vcc, exec, s[0:1]
	s_cbranch_vccz .LBB0_324
	s_cmp_gt_i32 s14, 3
	s_cselect_b64 s[8:9], -1, 0
	s_lshl_b32 s21, s14, 2
	s_sub_i32 s24, s21, 28
	s_cmp_gt_u32 s14, 6
	s_cselect_b64 s[0:1], -1, 0
	s_add_i32 s4, s21, s70
	s_waitcnt lgkmcnt(3)
	v_cndmask_b32_e64 v66, 0, 1, s[0:1]
	s_and_b32 s22, s4, 15
	s_mov_b64 s[10:11], -1
	s_and_b64 vcc, exec, s[8:9]
	v_cmp_ne_u32_e64 s[4:5], 1, v66
	s_cbranch_vccz .LBB0_263
	s_and_b64 vcc, exec, s[4:5]
	v_mov_b32_e32 v67, s22
	v_mov_b32_e32 v66, v234
	s_cbranch_vccnz .LBB0_262
	v_add_u32_e32 v66, s24, v228
	v_mul_u32_u24_e32 v67, 11, v66
	v_lshrrev_b32_e32 v67, 5, v67
	v_add3_u32 v66, v66, s65, v67
	v_and_b32_e32 v67, 15, v66
	v_mov_b32_e32 v66, s15

; __device__ __forceinline__ void run_desc(int tt, int g, int c, int R0, int& cg, int& Rg) {
;     if (tt < 4) { cg = c; Rg = R0 - 16 + 4 * tt + g; }
;     else if (tt < 7) { cg = (c + 4 * (tt - 3)) & 15; Rg = R0 - 4 + g; }
;     else if (tt < 10) { const int o = 4 * (tt - 7) + g; const int o3 = (o * 11) >> 5; cg = (c + 1 + o3 * 4 + (o - 3 * o3)) & 15; Rg = R0 - 1; }
;     else { cg = tt - 10; Rg = R0 + g; }
; __device__ __forceinline__ void attn_load_v(const AttnP& P, LAS unsigned char* lds, int hb, int tt, int c, int R0, int lane, bf16x8 (&vf)[2][2]) {
;     ...
;         for (int s = 0; s < 2; ++s) { int cg, Rg; run_desc(tt, 2 * s + h, c, R0, cg, Rg);
;             const bf16_t* vp = P.Vt + ((size_t)((hb * 16 + cg) * 16 + Rg) * 64 + rho) * 8;
;             vf[0][s] = *(const bf16x8*)(vp); vf[1][s] = *(const bf16x8*)(vp + 32 * 8); }
.LBB0_265:
	v_lshlrev_b32_e32 v67, 4, v67
	v_add3_u32 v66, v67, s20, v66
	v_ashrrev_i32_e32 v67, 31, v66
	v_lshlrev_b64 v[66:67], 10, v[66:67]
	v_lshl_add_u64 v[66:67], v[208:209], 0, v[66:67]
	global_load_dwordx4 v[162:165], v[66:67], off
	s_waitcnt lgkmcnt(2)
	global_load_dwordx4 v[158:161], v[66:67], off offset:512
	s_andn2_b64 vcc, exec, s[8:9]
	s_mov_b64 s[10:11], -1
	s_cbranch_vccnz .LBB0_269
	s_and_b64 vcc, exec, s[4:5]
	v_mov_b32_e32 v67, s22
	v_mov_b32_e32 v66, v236
	s_cbranch_vccnz .LBB0_268
	v_add_u32_e32 v66, s24, v235
	v_mul_u32_u24_e32 v67, 11, v66
	v_lshrrev_b32_e32 v67, 5, v67
	v_add3_u32 v66, v66, s65, v67
	v_and_b32_e32 v67, 15, v66
	v_mov_b32_e32 v66, s15

; __device__ __forceinline__ void run_desc(int tt, int g, int c, int R0, int& cg, int& Rg) {
;     if (tt < 4) { cg = c; Rg = R0 - 16 + 4 * tt + g; }
;     else if (tt < 7) { cg = (c + 4 * (tt - 3)) & 15; Rg = R0 - 4 + g; }
;     else if (tt < 10) { const int o = 4 * (tt - 7) + g; const int o3 = (o * 11) >> 5; cg = (c + 1 + o3 * 4 + (o - 3 * o3)) & 15; Rg = R0 - 1; }
;     else { cg = tt - 10; Rg = R0 + g; }
; __device__ __forceinline__ void attn_task(const AttnP& P, LAS unsigned char* lds, int b, int hd, int qq, int c, float shift, int lane_in) {
;     ...
;             } else {
;                 { int cg, Rg; run_desc(gi, h, c, R0, cg, Rg); w0 = (c > cg) ? mLp : mLn; }
;                 { int cg, Rg; run_desc(gi, 2 + h, c, R0, cg, Rg); w1 = (c > cg) ? mLp : mLn; }
.LBB0_271:
	v_lshlrev_b32_e32 v67, 4, v67
	v_add3_u32 v66, v67, s20, v66
	v_ashrrev_i32_e32 v67, 31, v66
	v_lshlrev_b64 v[66:67], 10, v[66:67]
	v_lshl_add_u64 v[66:67], v[208:209], 0, v[66:67]
	s_waitcnt lgkmcnt(1)
	global_load_dwordx4 v[166:169], v[66:67], off
	s_waitcnt lgkmcnt(0)
	global_load_dwordx4 v[170:173], v[66:67], off offset:512
	s_mov_b64 s[4:5], -1
	s_and_b64 vcc, exec, s[8:9]
	s_cbranch_vccz .LBB0_277
	s_and_b64 vcc, exec, s[0:1]
	s_cbranch_vccz .LBB0_274
	v_add_u32_e32 v66, s24, v228
	v_mul_u32_u24_e32 v67, 11, v66
	v_lshrrev_b32_e32 v67, 5, v67
	v_add3_u32 v66, v66, s65, v67
	v_and_b32_e32 v66, 15, v66
	v_cmp_gt_u32_e32 vcc, s64, v66
	v_add_u32_e32 v66, s21, v237
	v_mul_u32_u24_e32 v67, 11, v66
	v_lshrrev_b32_e32 v67, 5, v67
	v_add3_u32 v66, v66, s65, v67
	v_and_b32_e32 v66, 15, v66
	v_cndmask_b32_e32 v213, v153, v151, vcc
	v_cndmask_b32_e32 v212, v152, v150, vcc
	v_cmp_gt_u32_e32 vcc, s64, v66
	s_mov_b64 s[4:5], 0
	s_nop 0
	v_cndmask_b32_e32 v211, v153, v151, vcc
	v_cndmask_b32_e32 v210, v152, v150, vcc

; #define LAS __attribute__((address_space(3)))
; __device__ __forceinline__ int next_tile(int tt, int R0) { while (tt < 26 && !tile_valid(tt, R0)) ++tt; return tt; }
; __device__ __forceinline__ void attn_load_k(const AttnP& P, LAS unsigned char* lds, int hb, int tt, int c, int R0, int lane, bf16x8 (&kf)[4]) {
;     const int rho = lane & 31, h = lane >> 5;
;     const int gk_ = 2 * (rho >> 4) + ((rho >> 2) & 1), pk_ = 4 * ((rho >> 3) & 1) + (rho & 3);
;     if (tt < 10) {
;         int cg, Rg; run_desc(tt, gk_, c, R0, cg, Rg);
;         const bf16_t* kp = P.K + ((size_t)(hb * 16 + cg) * 128 + 8 * Rg + pk_) * 64 + 8 * h;
; #pragma unroll
;         for (int kk = 0; kk < 4; ++kk) kf[kk] = *(const bf16x8*)(kp + 16 * kk);
; __device__ __forceinline__ void attn_task(const AttnP& P, LAS unsigned char* lds, int b, int hd, int qq, int c, float shift, int lane_in) {
;     ...
;             gi = next_tile(gi + 1, R0);
;             if (gi < 10) attn_load_k(P, lds, hb, gi, c, R0, lane, gk);
.LBB0_283:
	s_add_i32 s0, s21, 4
	s_max_i32 s0, s0, s17
	s_not_b32 s1, s21
	s_add_i32 s0, s0, s1
	s_max_i32 s1, s14, 3
	s_lshr_b32 s0, s0, 2
	s_sub_i32 s1, s1, s14
	s_min_u32 s0, s0, s1
	s_add_i32 s0, s14, s0
	s_add_i32 s14, s0, 1
	s_waitcnt vmcnt(4)
	v_mov_b64_e32 v[184:185], v[108:109]
	v_mov_b64_e32 v[182:183], v[106:107]
	v_mov_b64_e32 v[176:177], v[132:133]
	v_mov_b64_e32 v[174:175], v[130:131]
	v_mov_b64_e32 v[180:181], v[128:129]
	v_mov_b64_e32 v[178:179], v[126:127]
	v_mov_b64_e32 v[68:69], v[112:113]
	v_mov_b64_e32 v[66:67], v[110:111]
	s_cmp_gt_i32 s0, 8
	s_cbranch_scc1 .Lattn_nopf_2
	s_lshl_b32 s4, s14, 2
	s_cmp_gt_i32 s0, 2
	s_mov_b64 s[0:1], -1
	s_cbranch_scc0 .LBB0_290
	s_cmp_gt_u32 s14, 6
	s_cbranch_scc0 .LBB0_287
	v_add_u32_e32 v70, s4, v17
	v_mul_u32_u24_e32 v71, 11, v70
	v_lshrrev_b32_e32 v71, 5, v71
	v_add3_u32 v70, v70, s65, v71
	v_and_b32_e32 v70, 15, v70
	s_mov_b64 s[0:1], 0

; __device__ __forceinline__ void run_desc(int tt, int g, int c, int R0, int& cg, int& Rg) {
;     if (tt < 4) { cg = c; Rg = R0 - 16 + 4 * tt + g; }
;     else if (tt < 7) { cg = (c + 4 * (tt - 3)) & 15; Rg = R0 - 4 + g; }
;     else if (tt < 10) { const int o = 4 * (tt - 7) + g; const int o3 = (o * 11) >> 5; cg = (c + 1 + o3 * 4 + (o - 3 * o3)) & 15; Rg = R0 - 1; }
;     else { cg = tt - 10; Rg = R0 + g; }
; __device__ __forceinline__ void attn_load_k(const AttnP& P, LAS unsigned char* lds, int hb, int tt, int c, int R0, int lane, bf16x8 (&kf)[4]) {
;     ...
;     if (tt < 10) {
;         int cg, Rg; run_desc(tt, gk_, c, R0, cg, Rg);
;         const bf16_t* kp = P.K + ((size_t)(hb * 16 + cg) * 128 + 8 * Rg + pk_) * 64 + 8 * h;
.LBB0_295:
	s_lshl_b32 s8, s19, 2
	s_cmp_gt_i32 s19, 3
	s_mov_b64 s[4:5], -1
	s_cbranch_scc0 .LBB0_301
	s_cmp_gt_u32 s19, 6
	s_cbranch_scc0 .LBB0_298
	s_waitcnt lgkmcnt(3)
	v_add_u32_e32 v66, s8, v17
	v_mul_u32_u24_e32 v67, 11, v66
	v_lshrrev_b32_e32 v67, 5, v67
	v_add3_u32 v66, v66, s65, v67
	v_and_b32_e32 v66, 15, v66
	s_mov_b64 s[4:5], 0

; __device__ __forceinline__ void run_desc(int tt, int g, int c, int R0, int& cg, int& Rg) {
;     if (tt < 4) { cg = c; Rg = R0 - 16 + 4 * tt + g; }
;     else if (tt < 7) { cg = (c + 4 * (tt - 3)) & 15; Rg = R0 - 4 + g; }
;     else if (tt < 10) { const int o = 4 * (tt - 7) + g; const int o3 = (o * 11) >> 5; cg = (c + 1 + o3 * 4 + (o - 3 * o3)) & 15; Rg = R0 - 1; }
;     else { cg = tt - 10; Rg = R0 + g; }
; __device__ __forceinline__ void attn_load_v(const AttnP& P, LAS unsigned char* lds, int hb, int tt, int c, int R0, int lane, bf16x8 (&vf)[2][2]) {
;     ...
;         for (int s = 0; s < 2; ++s) { int cg, Rg; run_desc(tt, 2 * s + h, c, R0, cg, Rg);
;             const bf16_t* vp = P.Vt + ((size_t)((hb * 16 + cg) * 16 + Rg) * 64 + rho) * 8;
.LBB0_305:
	s_cmp_gt_i32 s19, 3
	s_cselect_b64 s[0:1], -1, 0
	s_lshl_b32 s22, s19, 2
	s_sub_i32 s11, s22, 28
	s_cmp_gt_u32 s19, 6
	s_cselect_b64 s[4:5], -1, 0
	s_add_i32 s8, s22, s70
	v_cndmask_b32_e64 v70, 0, 1, s[4:5]
	s_and_b32 s21, s8, 15
	s_mov_b64 s[8:9], -1
	s_and_b64 vcc, exec, s[0:1]
	v_cmp_ne_u32_e64 s[4:5], 1, v70
	s_cbranch_vccz .LBB0_309
	s_and_b64 vcc, exec, s[4:5]
	v_mov_b32_e32 v71, s21
	v_mov_b32_e32 v70, v234
	s_cbranch_vccnz .LBB0_308
	v_add_u32_e32 v70, s11, v228
	v_mul_u32_u24_e32 v71, 11, v70
	v_lshrrev_b32_e32 v71, 5, v71
	v_add3_u32 v70, v70, s65, v71
	v_and_b32_e32 v71, 15, v70
	v_mov_b32_e32 v70, s15

; __device__ __forceinline__ void run_desc(int tt, int g, int c, int R0, int& cg, int& Rg) {
;     if (tt < 4) { cg = c; Rg = R0 - 16 + 4 * tt + g; }
;     else if (tt < 7) { cg = (c + 4 * (tt - 3)) & 15; Rg = R0 - 4 + g; }
;     else if (tt < 10) { const int o = 4 * (tt - 7) + g; const int o3 = (o * 11) >> 5; cg = (c + 1 + o3 * 4 + (o - 3 * o3)) & 15; Rg = R0 - 1; }
;     else { cg = tt - 10; Rg = R0 + g; }
; __device__ __forceinline__ void attn_load_v(const AttnP& P, LAS unsigned char* lds, int hb, int tt, int c, int R0, int lane, bf16x8 (&vf)[2][2]) {
;     ...
;         for (int s = 0; s < 2; ++s) { int cg, Rg; run_desc(tt, 2 * s + h, c, R0, cg, Rg);
;             const bf16_t* vp = P.Vt + ((size_t)((hb * 16 + cg) * 16 + Rg) * 64 + rho) * 8;
;             vf[0][s] = *(const bf16x8*)(vp); vf[1][s] = *(const bf16x8*)(vp + 32 * 8); }
.LBB0_311:
	v_lshlrev_b32_e32 v71, 4, v71
	v_add3_u32 v70, v71, s20, v70
	v_ashrrev_i32_e32 v71, 31, v70
	v_lshlrev_b64 v[70:71], 10, v[70:71]
	v_lshl_add_u64 v[70:71], v[208:209], 0, v[70:71]
	s_waitcnt lgkmcnt(3)
	global_load_dwordx4 v[162:165], v[70:71], off
	s_waitcnt lgkmcnt(2)
	global_load_dwordx4 v[158:161], v[70:71], off offset:512
	s_andn2_b64 vcc, exec, s[0:1]
	s_mov_b64 s[0:1], -1
	s_cbranch_vccnz .LBB0_315
	s_and_b64 vcc, exec, s[4:5]
	v_mov_b32_e32 v71, s21
	v_mov_b32_e32 v70, v236
	s_cbranch_vccnz .LBB0_314
	v_add_u32_e32 v70, s11, v235
	v_mul_u32_u24_e32 v71, 11, v70
	v_lshrrev_b32_e32 v71, 5, v71
	v_add3_u32 v70, v70, s65, v71
	v_and_b32_e32 v71, 15, v70
	v_mov_b32_e32 v70, s15

; __device__ __forceinline__ void attn_task(const AttnP& P, LAS unsigned char* lds, int b, int hd, int qq, int c, float shift, int lane_in) {
;     ...
;             const int dl = c - (li - 10);
;             if (dl == 0) { w0 = 3 * Hp[0] - Hn[0] + Bn[0]; w1 = 3 * Hp[1] - Hn[1] + Bn[1]; }
;             else if (dl > 0) { const unsigned long long m = ((dl & 3) == 0) ? ~0ull : 0ull; w0 = Bp[0] + (Hp[0] & m); w1 = Bp[1] + (Hp[1] & m); }
;             else { const unsigned long long m = ((dl & 3) == 0) ? ~0ull : 0ull; w0 = Bn[0] + (Hn[0] & m); w1 = Bn[1] + (Hn[1] & m); }
.LBB0_318:
	s_add_i32 s0, s19, -10
	s_cmp_eq_u32 s64, s0
	s_cbranch_scc1 .Latb1_own
	s_sub_i32 s4, s64, s0
	s_and_b32 s0, s4, 3
	s_cmp_lg_u32 s0, 0
	s_cbranch_scc1 .Latb1_pure
	s_cmp_lt_i32 s4, 1
	s_mov_b64 s[4:5], -1
	s_cbranch_scc0 .LBB0_321
	v_lshl_add_u64 v[212:213], v[114:115], 0, v[122:123]
	v_lshl_add_u64 v[210:211], v[116:117], 0, v[124:125]
	s_mov_b64 s[4:5], 0

; #define LAS __attribute__((address_space(3)))
; __device__ __forceinline__ int next_tile(int tt, int R0) { while (tt < 26 && !tile_valid(tt, R0)) ++tt; return tt; }
; __device__ __forceinline__ void attn_task(const AttnP& P, LAS unsigned char* lds, int b, int hd, int qq, int c, float shift, int lane_in) {
;     int lane = lane_in; asm volatile("" : "+v"(lane));
;     const int hb = b * 8 + hd, q = lane & 31, h = lane >> 5, R0 = 4 * qq, iq0 = 32 * qq;
;     bf16x8 qf[4];
;     { const bf16_t* qp = P.Q + ((size_t)(hb * 16 + c) * 128 + iq0 + q) * 64 + 8 * h;
; #pragma unroll
;       for (int kk = 0; kk < 4; ++kk) qf[kk] = *(const bf16x8*)(qp + 16 * kk); }
;     bf16x8 gk[4];
;     int gi = next_tile(0, R0);
;     if (gi < 10) attn_load_k(P, lds, hb, gi, c, R0, lane, gk);
;     unsigned long long Hp[2], Hn[2], Bp[2], Bn[2], mT0[2], mT3[2], mAp[2], mAn[2], mLp, mLn;
;     { const LAS unsigned long long* T = (const LAS unsigned long long*)(lds + LDS_ATAB + lane * 144);
;       Hp[0] = T[0]; Hp[1] = T[1]; Hn[0] = T[2]; Hn[1] = T[3]; Bp[0] = T[4]; Bp[1] = T[5]; Bn[0] = T[6]; Bn[1] = T[7];
;       mT0[0] = T[8]; mT0[1] = T[9]; mT3[0] = T[10]; mT3[1] = T[11]; mAp[0] = T[12]; mAp[1] = T[13]; mAn[0] = T[14]; mAn[1] = T[15]; mLp = T[16]; mLn = T[17]; }
;     f32x16 o0 = {}, o1 = {}, zacc = {};
;     bf16x8 ones = {0x3F80, 0x3F80, 0x3F80, 0x3F80, 0x3F80, 0x3F80, 0x3F80, 0x3F80}; asm volatile("" : "+v"(ones));
;     int li = 10, ph = 0;
; __device__ __forceinline__ void attn_unit(const AttnP& P, LAS unsigned char* lds, int b, int hd, int qq, int wave, int lane) {
;     ...
;     { const float mq = wave_max(fabsf(P.gq[lane])), mk = wave_max(fabsf(P.gk[lane])); shift = fminf(8.0f * mq * mk * 1.4426950408889634f, 64.0f); shift = shift > 30.0f ? shift : 0.f; }
.LBB0_333:
	s_waitcnt lgkmcnt(1)
	v_max_f32_e32 v7, v7, v7
	v_max_f32_e32 v2, v2, v7
	s_waitcnt lgkmcnt(0)
	v_max_f32_e32 v7, v8, v8
	v_max_f32_e32 v6, v6, v7
	v_mul_f32_e32 v2, 0x41000000, v2
	v_mul_f32_e32 v2, v2, v6
	v_mul_lo_u32 v6, v228, s31
	v_add_u32_e32 v6, 0, v6
	v_mul_f32_e32 v2, 0x3fb8aa3b, v2
	v_add_u32_e32 v6, 0x24000, v6
	v_min_f32_e32 v2, 0x42800000, v2
	ds_read_b128 v[118:121], v6
	ds_read_b128 v[122:125], v6 offset:16
	ds_read_b128 v[126:129], v6 offset:32
	ds_read_b128 v[130:133], v6 offset:48
	ds_read_b128 v[134:137], v6 offset:64
	ds_read_b128 v[138:141], v6 offset:80
	ds_read_b128 v[142:145], v6 offset:96
	ds_read_b128 v[146:149], v6 offset:112
	ds_read_b128 v[150:153], v6 offset:128
	s_waitcnt lgkmcnt(8)
	v_mad_u64_u32 v[8:9], s[0:1], v118, 3, 0
	v_cmp_lt_f32_e32 vcc, s30, v2
	v_mov_b32_e32 v10, v9
	v_mad_u64_u32 v[10:11], s[0:1], v119, 3, v[10:11]
	v_cndmask_b32_e32 v2, 0, v2, vcc
	s_nop 0
	v_readfirstlane_b32 s100, v2
	s_nop 1
	v_cmp_class_f32_e64 s[100:101], s100, 64
	s_waitcnt lgkmcnt(7)
	v_sub_co_u32_e32 v8, vcc, v8, v122
	s_lshl_b32 s56, s12, 2
	s_nop 0
	v_subb_co_u32_e32 v9, vcc, v10, v123, vcc
	s_waitcnt lgkmcnt(5)
	v_lshl_add_u64 v[202:203], v[8:9], 0, v[130:131]
	v_mad_u64_u32 v[8:9], s[0:1], v120, 3, 0
	s_xor_b32 s39, s56, 15
	v_mov_b32_e32 v10, v9
	s_and_b64 s[0:1], exec, s[60:61]
	v_mad_u64_u32 v[10:11], s[0:1], v121, 3, v[10:11]
	v_sub_co_u32_e32 v8, vcc, v8, v124
	v_mov_b32_e32 v18, 0
	s_cselect_b32 s24, 3, 10
	v_mov_b64_e32 v[156:157], v[84:85]
	s_add_i32 s57, s56, -4
	s_or_b32 s49, s56, -16
	v_lshlrev_b32_e32 v6, 4, v229
	v_add_u32_e32 v230, 2, v17
	v_subb_co_u32_e32 v9, vcc, v10, v125, vcc
	v_mov_b32_e32 v7, v191
	s_mov_b32 s66, 10
	v_mov_b64_e32 v[154:155], v[82:83]
	v_lshl_add_u32 v200, v17, 4, 0
	v_or_b32_e32 v223, 0xffffffe4, v1
	s_add_i32 s48, s56, -1
	v_or_b32_e32 v224, s57, v1
	v_or_b32_e32 v225, s49, v1
	v_add_u32_e32 v226, s93, v6
	v_add_u32_e32 v227, s57, v17
	v_add_u32_e32 v231, s57, v230
	v_lshl_add_u64 v[204:205], v[8:9], 0, v[132:133]
	v_subrev_u32_e32 v232, 26, v17
	v_lshl_add_u32 v233, v17, 10, v214
	v_or3_b32 v234, v190, v3, s36
	v_lshl_add_u64 v[206:207], v[4:5], 1, s[50:51]
	v_lshl_add_u64 v[208:209], s[52:53], 0, v[6:7]
	s_mov_b32 s87, s39
	s_mov_b32 s86, s39
	s_mov_b32 s22, s39
	s_mov_b32 s23, s39
	s_mov_b32 s94, s39
	s_mov_b32 s95, s39
	s_mov_b32 s96, s39
	v_mov_b32_e32 v1, v2
	v_mov_b32_e32 v4, v2
	v_mov_b32_e32 v3, v2
	v_mov_b32_e32 v6, v2
	v_mov_b32_e32 v5, v2
	v_mov_b32_e32 v8, v2
	v_mov_b32_e32 v7, v2
	s_mov_b32 s8, 0
	s_mov_b64 s[0:1], s[60:61]
	s_mov_b32 s72, s24
	v_mov_b32_e32 v19, v18
	v_mov_b32_e32 v20, v18
	v_mov_b32_e32 v21, v18
	v_mov_b32_e32 v22, v18
	v_mov_b32_e32 v23, v18
	v_mov_b32_e32 v24, v18
	v_mov_b32_e32 v25, v18
	v_mov_b32_e32 v26, v18
	v_mov_b32_e32 v27, v18
	v_mov_b32_e32 v28, v18
	v_mov_b32_e32 v29, v18
	v_mov_b32_e32 v30, v18
	v_mov_b32_e32 v31, v18
	v_mov_b32_e32 v32, v18
	v_mov_b32_e32 v33, v18
	v_mov_b32_e32 v34, v18
	v_mov_b32_e32 v35, v18
	v_mov_b32_e32 v36, v18
	v_mov_b32_e32 v37, v18
	v_mov_b32_e32 v38, v18
	v_mov_b32_e32 v39, v18
	v_mov_b32_e32 v40, v18
	v_mov_b32_e32 v41, v18
	v_mov_b32_e32 v42, v18
	v_mov_b32_e32 v43, v18
	v_mov_b32_e32 v44, v18
	v_mov_b32_e32 v45, v18
	v_mov_b32_e32 v46, v18
	v_mov_b32_e32 v47, v18
	v_mov_b32_e32 v48, v18
	v_mov_b32_e32 v49, v18
	v_mov_b32_e32 v50, v18
	v_mov_b32_e32 v51, v18
	v_mov_b32_e32 v52, v18
	v_mov_b32_e32 v53, v18
	v_mov_b32_e32 v54, v18
	v_mov_b32_e32 v55, v18
	v_mov_b32_e32 v56, v18
	v_mov_b32_e32 v57, v18
	v_mov_b32_e32 v58, v18
	v_mov_b32_e32 v59, v18
	v_mov_b32_e32 v60, v18
	v_mov_b32_e32 v61, v18
	v_mov_b32_e32 v62, v18
	v_mov_b32_e32 v63, v18
	v_mov_b32_e32 v64, v18
	v_mov_b32_e32 v65, v18
	v_mov_b32_e32 v10, v2
	v_mov_b32_e32 v9, v2
	v_mov_b32_e32 v12, v2
	v_mov_b32_e32 v11, v2
	v_mov_b32_e32 v14, v2
	v_mov_b32_e32 v13, v2
	v_mov_b32_e32 v16, v2
	v_mov_b32_e32 v15, v2
	v_mul_lo_u32 v245, v234, s71
	v_add_u32_e32 v245, v245, v200
	s_branch .LBB0_335

; #define LAS __attribute__((address_space(3)))
; __device__ __forceinline__ void attn_load_k(const AttnP& P, LAS unsigned char* lds, int hb, int tt, int c, int R0, int lane, bf16x8 (&kf)[4]) {
;     ...
;     } else {
;         const LAS unsigned char* kp = lds + LDS_KC + ((tt - 10) * 32 + 8 * gk_ + pk_) * KC_PITCH + 16 * h;
; #pragma unroll
;         for (int kk = 0; kk < 4; ++kk) kf[kk] = *(const LAS bf16x8*)(kp + 32 * kk);
.LBB0_337:
	s_andn2_b64 vcc, exec, s[4:5]
	s_cbranch_vccnz .LBB0_342
	s_cmp_gt_i32 s66, 9
	s_cselect_b64 s[0:1], -1, 0
	s_mov_b64 s[4:5], -1
	s_and_b64 vcc, exec, s[0:1]
	s_cbranch_vccz .LBB0_373
	s_mul_i32 s4, s66, 0x1400
	v_add_u32_e32 v70, s4, v245
	ds_read_b128 v[66:69], v70
	ds_read_b128 v[178:181], v70 offset:32
	ds_read_b128 v[174:177], v70 offset:64
	ds_read_b128 v[182:185], v70 offset:96
	s_cbranch_execz .LBB0_374

; __device__ __forceinline__ void run_desc(int tt, int g, int c, int R0, int& cg, int& Rg) {
;     if (tt < 4) { cg = c; Rg = R0 - 16 + 4 * tt + g; }
;     else if (tt < 7) { cg = (c + 4 * (tt - 3)) & 15; Rg = R0 - 4 + g; }
;     else if (tt < 10) { const int o = 4 * (tt - 7) + g; const int o3 = (o * 11) >> 5; cg = (c + 1 + o3 * 4 + (o - 3 * o3)) & 15; Rg = R0 - 1; }
;     else { cg = tt - 10; Rg = R0 + g; }
; __device__ __forceinline__ void attn_load_v(const AttnP& P, LAS unsigned char* lds, int hb, int tt, int c, int R0, int lane, bf16x8 (&vf)[2][2]) {
;     ...
;         for (int s = 0; s < 2; ++s) { int cg, Rg; run_desc(tt, 2 * s + h, c, R0, cg, Rg);
;             const bf16_t* vp = P.Vt + ((size_t)((hb * 16 + cg) * 16 + Rg) * 64 + rho) * 8;
.LBB0_342:
	s_and_b64 vcc, exec, s[0:1]
	s_cbranch_vccz .LBB0_403
	s_cmp_gt_i32 s72, 3
	s_cselect_b64 s[6:7], -1, 0
	s_lshl_b32 s68, s72, 2
	s_sub_i32 s11, s68, 28
	s_cmp_gt_u32 s72, 6
	s_cselect_b64 s[0:1], -1, 0
	s_add_i32 s4, s68, s63
	s_waitcnt vmcnt(3) lgkmcnt(3)
	v_cndmask_b32_e64 v66, 0, 1, s[0:1]
	s_and_b32 s10, s4, 15
	s_mov_b64 s[8:9], -1
	s_and_b64 vcc, exec, s[6:7]
	v_cmp_ne_u32_e64 s[4:5], 1, v66
	s_cbranch_vccz .LBB0_347
	s_and_b64 vcc, exec, s[4:5]
	v_mov_b32_e32 v67, s10
	v_mov_b32_e32 v66, v227
	s_cbranch_vccnz .LBB0_346
	v_add_u32_e32 v66, s11, v17
	v_mul_u32_u24_e32 v67, 11, v66
	v_lshrrev_b32_e32 v67, 5, v67
	v_add3_u32 v66, v66, s62, v67
	v_and_b32_e32 v67, 15, v66
	v_mov_b32_e32 v66, s48

; __device__ __forceinline__ void run_desc(int tt, int g, int c, int R0, int& cg, int& Rg) {
;     if (tt < 4) { cg = c; Rg = R0 - 16 + 4 * tt + g; }
;     else if (tt < 7) { cg = (c + 4 * (tt - 3)) & 15; Rg = R0 - 4 + g; }
;     else if (tt < 10) { const int o = 4 * (tt - 7) + g; const int o3 = (o * 11) >> 5; cg = (c + 1 + o3 * 4 + (o - 3 * o3)) & 15; Rg = R0 - 1; }
;     else { cg = tt - 10; Rg = R0 + g; }
; __device__ __forceinline__ void attn_load_v(const AttnP& P, LAS unsigned char* lds, int hb, int tt, int c, int R0, int lane, bf16x8 (&vf)[2][2]) {
;     ...
;         for (int s = 0; s < 2; ++s) { int cg, Rg; run_desc(tt, 2 * s + h, c, R0, cg, Rg);
;             const bf16_t* vp = P.Vt + ((size_t)((hb * 16 + cg) * 16 + Rg) * 64 + rho) * 8;
;             vf[0][s] = *(const bf16x8*)(vp); vf[1][s] = *(const bf16x8*)(vp + 32 * 8); }
.LBB0_349:
	v_lshlrev_b32_e32 v67, 4, v67
	v_add3_u32 v66, v67, s20, v66
	v_ashrrev_i32_e32 v67, 31, v66
	v_lshlrev_b64 v[66:67], 10, v[66:67]
	v_lshl_add_u64 v[66:67], v[208:209], 0, v[66:67]
	global_load_dwordx4 v[162:165], v[66:67], off
	s_waitcnt lgkmcnt(2)
	global_load_dwordx4 v[158:161], v[66:67], off offset:512
	s_andn2_b64 vcc, exec, s[6:7]
	s_mov_b64 s[8:9], -1
	s_cbranch_vccnz .LBB0_353
	s_and_b64 vcc, exec, s[4:5]
	v_mov_b32_e32 v67, s10
	v_mov_b32_e32 v66, v231
	s_cbranch_vccnz .LBB0_352
	v_add_u32_e32 v66, s11, v230
	v_mul_u32_u24_e32 v67, 11, v66
	v_lshrrev_b32_e32 v67, 5, v67
	v_add3_u32 v66, v66, s62, v67
	v_and_b32_e32 v67, 15, v66
	v_mov_b32_e32 v66, s48

; __device__ __forceinline__ void run_desc(int tt, int g, int c, int R0, int& cg, int& Rg) {
;     if (tt < 4) { cg = c; Rg = R0 - 16 + 4 * tt + g; }
;     else if (tt < 7) { cg = (c + 4 * (tt - 3)) & 15; Rg = R0 - 4 + g; }
;     else if (tt < 10) { const int o = 4 * (tt - 7) + g; const int o3 = (o * 11) >> 5; cg = (c + 1 + o3 * 4 + (o - 3 * o3)) & 15; Rg = R0 - 1; }
;     else { cg = tt - 10; Rg = R0 + g; }
; __device__ __forceinline__ void attn_task(const AttnP& P, LAS unsigned char* lds, int b, int hd, int qq, int c, float shift, int lane_in) {
;     ...
;             } else {
;                 { int cg, Rg; run_desc(gi, h, c, R0, cg, Rg); w0 = (c > cg) ? mLp : mLn; }
;                 { int cg, Rg; run_desc(gi, 2 + h, c, R0, cg, Rg); w1 = (c > cg) ? mLp : mLn; }
.LBB0_355:
	v_lshlrev_b32_e32 v67, 4, v67
	v_add3_u32 v66, v67, s20, v66
	v_ashrrev_i32_e32 v67, 31, v66
	v_lshlrev_b64 v[66:67], 10, v[66:67]
	v_lshl_add_u64 v[66:67], v[208:209], 0, v[66:67]
	s_waitcnt lgkmcnt(1)
	global_load_dwordx4 v[166:169], v[66:67], off
	s_waitcnt lgkmcnt(0)
	global_load_dwordx4 v[170:173], v[66:67], off offset:512
	s_mov_b64 s[4:5], -1
	s_and_b64 vcc, exec, s[6:7]
	s_cbranch_vccz .LBB0_361
	s_and_b64 vcc, exec, s[0:1]
	s_cbranch_vccz .LBB0_358
	v_add_u32_e32 v66, s11, v17
	v_mul_u32_u24_e32 v67, 11, v66
	v_lshrrev_b32_e32 v67, 5, v67
	v_add3_u32 v66, v66, s62, v67
	v_and_b32_e32 v66, 15, v66
	v_cmp_gt_u32_e32 vcc, s92, v66
	v_add_u32_e32 v66, s68, v232
	v_mul_u32_u24_e32 v67, 11, v66
	v_lshrrev_b32_e32 v67, 5, v67
	v_add3_u32 v66, v66, s62, v67
	v_and_b32_e32 v66, 15, v66
	v_cndmask_b32_e32 v213, v153, v151, vcc
	v_cndmask_b32_e32 v212, v152, v150, vcc
	v_cmp_gt_u32_e32 vcc, s92, v66
	s_mov_b64 s[4:5], 0
	s_nop 0
	v_cndmask_b32_e32 v211, v153, v151, vcc
	v_cndmask_b32_e32 v210, v152, v150, vcc

; __device__ __forceinline__ void run_desc(int tt, int g, int c, int R0, int& cg, int& Rg) {
;     if (tt < 4) { cg = c; Rg = R0 - 16 + 4 * tt + g; }
;     else if (tt < 7) { cg = (c + 4 * (tt - 3)) & 15; Rg = R0 - 4 + g; }
;     else if (tt < 10) { const int o = 4 * (tt - 7) + g; const int o3 = (o * 11) >> 5; cg = (c + 1 + o3 * 4 + (o - 3 * o3)) & 15; Rg = R0 - 1; }
;     else { cg = tt - 10; Rg = R0 + g; }
; __device__ __forceinline__ void attn_load_k(const AttnP& P, LAS unsigned char* lds, int hb, int tt, int c, int R0, int lane, bf16x8 (&kf)[4]) {
;     ...
;     if (tt < 10) {
;         int cg, Rg; run_desc(tt, gk_, c, R0, cg, Rg);
;         const bf16_t* kp = P.K + ((size_t)(hb * 16 + cg) * 128 + 8 * Rg + pk_) * 64 + 8 * h;
.LBB0_374:
	s_lshl_b32 s6, s66, 2
	s_cmp_gt_i32 s66, 3
	s_mov_b64 s[4:5], -1
	s_cbranch_scc0 .LBB0_380
	s_cmp_gt_u32 s66, 6
	s_cbranch_scc0 .LBB0_377
	s_waitcnt lgkmcnt(3)
	v_add_u32_e32 v66, s6, v223
	v_mul_u32_u24_e32 v67, 11, v66
	v_lshrrev_b32_e32 v67, 5, v67
	v_add3_u32 v66, v66, s62, v67
	v_and_b32_e32 v66, 15, v66
	s_mov_b64 s[4:5], 0

; __device__ __forceinline__ void run_desc(int tt, int g, int c, int R0, int& cg, int& Rg) {
;     if (tt < 4) { cg = c; Rg = R0 - 16 + 4 * tt + g; }
;     else if (tt < 7) { cg = (c + 4 * (tt - 3)) & 15; Rg = R0 - 4 + g; }
;     else if (tt < 10) { const int o = 4 * (tt - 7) + g; const int o3 = (o * 11) >> 5; cg = (c + 1 + o3 * 4 + (o - 3 * o3)) & 15; Rg = R0 - 1; }
;     else { cg = tt - 10; Rg = R0 + g; }
; __device__ __forceinline__ void attn_load_v(const AttnP& P, LAS unsigned char* lds, int hb, int tt, int c, int R0, int lane, bf16x8 (&vf)[2][2]) {
;     ...
;         for (int s = 0; s < 2; ++s) { int cg, Rg; run_desc(tt, 2 * s + h, c, R0, cg, Rg);
;             const bf16_t* vp = P.Vt + ((size_t)((hb * 16 + cg) * 16 + Rg) * 64 + rho) * 8;
.LBB0_384:
	s_cmp_gt_i32 s66, 3
	s_cselect_b64 s[0:1], -1, 0
	s_lshl_b32 s11, s66, 2
	s_sub_i32 s9, s11, 28
	s_cmp_gt_u32 s66, 6
	s_cselect_b64 s[4:5], -1, 0
	s_add_i32 s6, s11, s63
	v_cndmask_b32_e64 v70, 0, 1, s[4:5]
	s_and_b32 s10, s6, 15
	s_mov_b64 s[6:7], -1
	s_and_b64 vcc, exec, s[0:1]
	v_cmp_ne_u32_e64 s[4:5], 1, v70
	s_cbranch_vccz .LBB0_388
	s_and_b64 vcc, exec, s[4:5]
	v_mov_b32_e32 v71, s10
	v_mov_b32_e32 v70, v227
	s_cbranch_vccnz .LBB0_387
	v_add_u32_e32 v70, s9, v17
	v_mul_u32_u24_e32 v71, 11, v70
	v_lshrrev_b32_e32 v71, 5, v71
	v_add3_u32 v70, v70, s62, v71
	v_and_b32_e32 v71, 15, v70
	v_mov_b32_e32 v70, s48

; __device__ __forceinline__ void run_desc(int tt, int g, int c, int R0, int& cg, int& Rg) {
;     if (tt < 4) { cg = c; Rg = R0 - 16 + 4 * tt + g; }
;     else if (tt < 7) { cg = (c + 4 * (tt - 3)) & 15; Rg = R0 - 4 + g; }
;     else if (tt < 10) { const int o = 4 * (tt - 7) + g; const int o3 = (o * 11) >> 5; cg = (c + 1 + o3 * 4 + (o - 3 * o3)) & 15; Rg = R0 - 1; }
;     else { cg = tt - 10; Rg = R0 + g; }
; __device__ __forceinline__ void attn_load_v(const AttnP& P, LAS unsigned char* lds, int hb, int tt, int c, int R0, int lane, bf16x8 (&vf)[2][2]) {
;     ...
;         for (int s = 0; s < 2; ++s) { int cg, Rg; run_desc(tt, 2 * s + h, c, R0, cg, Rg);
;             const bf16_t* vp = P.Vt + ((size_t)((hb * 16 + cg) * 16 + Rg) * 64 + rho) * 8;
;             vf[0][s] = *(const bf16x8*)(vp); vf[1][s] = *(const bf16x8*)(vp + 32 * 8); }
.LBB0_390:
	v_lshlrev_b32_e32 v71, 4, v71
	v_add3_u32 v70, v71, s20, v70
	v_ashrrev_i32_e32 v71, 31, v70
	v_lshlrev_b64 v[70:71], 10, v[70:71]
	v_lshl_add_u64 v[70:71], v[208:209], 0, v[70:71]
	s_waitcnt lgkmcnt(3)
	global_load_dwordx4 v[162:165], v[70:71], off
	s_waitcnt lgkmcnt(2)
	global_load_dwordx4 v[158:161], v[70:71], off offset:512
	s_andn2_b64 vcc, exec, s[0:1]
	s_mov_b64 s[0:1], -1
	s_cbranch_vccnz .LBB0_394
	s_and_b64 vcc, exec, s[4:5]
	v_mov_b32_e32 v71, s10
	v_mov_b32_e32 v70, v231
	s_cbranch_vccnz .LBB0_393
	v_add_u32_e32 v70, s9, v230
	v_mul_u32_u24_e32 v71, 11, v70
	v_lshrrev_b32_e32 v71, 5, v71
	v_add3_u32 v70, v70, s62, v71
	v_and_b32_e32 v71, 15, v70
	v_mov_b32_e32 v70, s48

; __device__ __forceinline__ void attn_task(const AttnP& P, LAS unsigned char* lds, int b, int hd, int qq, int c, float shift, int lane_in) {
;     ...
;             const int dl = c - (li - 10);
;             if (dl == 0) { w0 = 3 * Hp[0] - Hn[0] + Bn[0]; w1 = 3 * Hp[1] - Hn[1] + Bn[1]; }
;             else if (dl > 0) { const unsigned long long m = ((dl & 3) == 0) ? ~0ull : 0ull; w0 = Bp[0] + (Hp[0] & m); w1 = Bp[1] + (Hp[1] & m); }
;             else { const unsigned long long m = ((dl & 3) == 0) ? ~0ull : 0ull; w0 = Bn[0] + (Hn[0] & m); w1 = Bn[1] + (Hn[1] & m); }
.LBB0_397:
	s_add_i32 s0, s66, -10
	s_cmp_eq_u32 s92, s0
	s_cbranch_scc1 .Latb2_own
	s_sub_i32 s4, s92, s0
	s_and_b32 s0, s4, 3
	s_cmp_lg_u32 s0, 0
	s_cbranch_scc1 .Latb2_pure
	s_cmp_lt_i32 s4, 1
	s_mov_b64 s[4:5], -1
	s_cbranch_scc0 .LBB0_400
	v_lshl_add_u64 v[212:213], v[122:123], 0, v[130:131]
	v_lshl_add_u64 v[210:211], v[124:125], 0, v[132:133]
	s_mov_b64 s[4:5], 0
.LBB0_400:
	s_andn2_b64 vcc, exec, s[4:5]
	s_cbranch_vccnz .LBB0_402
	v_lshl_add_u64 v[212:213], v[118:119], 0, v[126:127]
	v_lshl_add_u64 v[210:211], v[120:121], 0, v[128:129]
	s_branch .LBB0_402

; __device__ __forceinline__ void attn_task(const AttnP& P, LAS unsigned char* lds, int b, int hd, int qq, int c, float shift, int lane_in) {
;     ...
;             const int dl = c - (li - 10);
;             if (dl == 0) { w0 = 3 * Hp[0] - Hn[0] + Bn[0]; w1 = 3 * Hp[1] - Hn[1] + Bn[1]; }
;             else if (dl > 0) { const unsigned long long m = ((dl & 3) == 0) ? ~0ull : 0ull; w0 = Bp[0] + (Hp[0] & m); w1 = Bp[1] + (Hp[1] & m); }
;             else { const unsigned long long m = ((dl & 3) == 0) ? ~0ull : 0ull; w0 = Bn[0] + (Hn[0] & m); w1 = Bn[1] + (Hn[1] & m); }
.Latb2_pure:
	s_cmp_lt_i32 s4, 1
	s_cbranch_scc1 .Latb2_pneg
	v_mov_b64_e32 v[212:213], v[126:127]
	v_mov_b64_e32 v[210:211], v[128:129]
	s_branch .LBB0_402
.Latb2_pneg:
	v_mov_b64_e32 v[212:213], v[130:131]
	v_mov_b64_e32 v[210:211], v[132:133]

; #define LAS __attribute__((address_space(3)))
; __device__ __forceinline__ int next_tile(int tt, int R0) { while (tt < 26 && !tile_valid(tt, R0)) ++tt; return tt; }
; __device__ __forceinline__ void attn_load_k(const AttnP& P, LAS unsigned char* lds, int hb, int tt, int c, int R0, int lane, bf16x8 (&kf)[4]) {
;     const int rho = lane & 31, h = lane >> 5;
;     const int gk_ = 2 * (rho >> 4) + ((rho >> 2) & 1), pk_ = 4 * ((rho >> 3) & 1) + (rho & 3);
;     if (tt < 10) {
;         int cg, Rg; run_desc(tt, gk_, c, R0, cg, Rg);
;         const bf16_t* kp = P.K + ((size_t)(hb * 16 + cg) * 128 + 8 * Rg + pk_) * 64 + 8 * h;
; #pragma unroll
;         for (int kk = 0; kk < 4; ++kk) kf[kk] = *(const bf16x8*)(kp + 16 * kk);
; __device__ __forceinline__ void attn_task(const AttnP& P, LAS unsigned char* lds, int b, int hd, int qq, int c, float shift, int lane_in) {
;     ...
;             gi = next_tile(gi + 1, R0);
;             if (gi < 10) attn_load_k(P, lds, hb, gi, c, R0, lane, gk);
.LBB0_417:
	v_mov_b64_e32 v[70:71], v[106:107]
	s_waitcnt vmcnt(6)
	v_mov_b64_e32 v[74:75], v[110:111]
	s_waitcnt vmcnt(5)
	v_mov_b64_e32 v[78:79], v[114:115]
	s_waitcnt vmcnt(4)
	v_mov_b64_e32 v[188:189], v[104:105]
	s_cmp_gt_i32 s36, 9
	v_mov_b64_e32 v[72:73], v[108:109]
	v_mov_b64_e32 v[76:77], v[112:113]
	v_mov_b64_e32 v[80:81], v[116:117]
	v_mov_b64_e32 v[186:187], v[102:103]
	s_cbranch_scc1 .LBB0_427
	s_lshl_b32 s4, s36, 2
	s_cmp_gt_i32 s36, 3
	s_mov_b64 s[0:1], -1
	s_cbranch_scc0 .LBB0_424
	s_cmp_gt_u32 s36, 6
	s_cbranch_scc0 .LBB0_421
	v_add_u32_e32 v66, s4, v223
	v_mul_u32_u24_e32 v67, 11, v66
	v_lshrrev_b32_e32 v67, 5, v67
	v_add3_u32 v66, v66, s62, v67
	v_and_b32_e32 v66, 15, v66
	s_mov_b64 s[0:1], 0

; __device__ __forceinline__ void tile_compute(const bf16x8 (&kf)[4], const bf16x8 (&vf)[2][2], const bf16x8 (&qf)[4], unsigned long long w0, unsigned long long w1,
;                                              float shift, f32x16& o0, f32x16& o1, f32x16& zacc, const bf16x8& ones) {
;     f32x16 st = {};
; #pragma unroll
;     for (int kk = 0; kk < 4; ++kk) st = __builtin_amdgcn_mfma_f32_32x32x16_bf16(kf[kk], qf[kk], st, 0, 0, 0);
;     if (__builtin_amdgcn_readfirstlane(__builtin_bit_cast(int, shift)) != 0) {
;         asm volatile("" ::: "memory");
; #pragma unroll
;         for (int e = 0; e < 16; ++e) st[e] -= shift;
;     }
.LBB0_428:
	s_waitcnt vmcnt(3) lgkmcnt(3)
	v_mfma_f32_32x32x16_bf16 v[66:81], v[66:69], v[86:89], 0
	s_and_b64 vcc, exec, s[100:101]
	s_waitcnt vmcnt(2) lgkmcnt(2)
	v_mfma_f32_32x32x16_bf16 v[66:81], v[178:181], v[90:93], v[66:81]
	s_waitcnt vmcnt(1) lgkmcnt(1)
	v_mfma_f32_32x32x16_bf16 v[66:81], v[174:177], v[94:97], v[66:81]
	s_waitcnt vmcnt(0) lgkmcnt(0)
	v_mfma_f32_32x32x16_bf16 v[66:81], v[182:185], v[98:101], v[66:81]
	s_cbranch_vccnz .LBB0_334
	s_nop 10
	v_sub_f32_e32 v81, v81, v15
	v_sub_f32_e32 v80, v80, v16
	v_sub_f32_e32 v79, v79, v13
	v_sub_f32_e32 v78, v78, v14
	v_sub_f32_e32 v77, v77, v11
	v_sub_f32_e32 v76, v76, v12
	v_sub_f32_e32 v75, v75, v9
	v_sub_f32_e32 v74, v74, v10
	v_sub_f32_e32 v73, v73, v7
	v_sub_f32_e32 v72, v72, v8
	v_sub_f32_e32 v71, v71, v5
	v_sub_f32_e32 v70, v70, v6
	v_sub_f32_e32 v69, v69, v3
	v_sub_f32_e32 v68, v68, v4
	v_sub_f32_e32 v67, v67, v1
	v_sub_f32_e32 v66, v66, v2
	s_branch .LBB0_334

; #define LAS __attribute__((address_space(3)))
; __device__ __forceinline__ int next_tile(int tt, int R0) { while (tt < 26 && !tile_valid(tt, R0)) ++tt; return tt; }
; __device__ __forceinline__ void attn_load_k(const AttnP& P, LAS unsigned char* lds, int hb, int tt, int c, int R0, int lane, bf16x8 (&kf)[4]) {
;     ...
;         const LAS unsigned char* kp = lds + LDS_KC + ((tt - 10) * 32 + 8 * gk_ + pk_) * KC_PITCH + 16 * h;
; __device__ __forceinline__ void attn_task(const AttnP& P, LAS unsigned char* lds, int b, int hd, int qq, int c, float shift, int lane_in) {
;     int lane = lane_in; asm volatile("" : "+v"(lane));
;     const int hb = b * 8 + hd, q = lane & 31, h = lane >> 5, R0 = 4 * qq, iq0 = 32 * qq;
;     bf16x8 qf[4];
;     { const bf16_t* qp = P.Q + ((size_t)(hb * 16 + c) * 128 + iq0 + q) * 64 + 8 * h;
; #pragma unroll
;       for (int kk = 0; kk < 4; ++kk) qf[kk] = *(const bf16x8*)(qp + 16 * kk); }
;     bf16x8 gk[4];
;     int gi = next_tile(0, R0);
;     if (gi < 10) attn_load_k(P, lds, hb, gi, c, R0, lane, gk);
;     unsigned long long Hp[2], Hn[2], Bp[2], Bn[2], mT0[2], mT3[2], mAp[2], mAn[2], mLp, mLn;
;     { const LAS unsigned long long* T = (const LAS unsigned long long*)(lds + LDS_ATAB + lane * 144);
;       Hp[0] = T[0]; Hp[1] = T[1]; Hn[0] = T[2]; Hn[1] = T[3]; Bp[0] = T[4]; Bp[1] = T[5]; Bn[0] = T[6]; Bn[1] = T[7];
;       mT0[0] = T[8]; mT0[1] = T[9]; mT3[0] = T[10]; mT3[1] = T[11]; mAp[0] = T[12]; mAp[1] = T[13]; mAn[0] = T[14]; mAn[1] = T[15]; mLp = T[16]; mLn = T[17]; }
;     f32x16 o0 = {}, o1 = {}, zacc = {};
;     bf16x8 ones = {0x3F80, 0x3F80, 0x3F80, 0x3F80, 0x3F80, 0x3F80, 0x3F80, 0x3F80}; asm volatile("" : "+v"(ones));
;     int li = 10, ph = 0;
.LBB0_436:
	s_movk_i32 s0, 0x90
	v_mul_lo_u32 v17, v224, s0
	v_add_u32_e32 v17, 0, v17
	v_add_u32_e32 v17, 0x24000, v17
	ds_read_b128 v[118:121], v17
	ds_read_b128 v[122:125], v17 offset:16
	ds_read_b128 v[126:129], v17 offset:32
	ds_read_b128 v[130:133], v17 offset:48
	ds_read_b128 v[134:137], v17 offset:64
	ds_read_b128 v[138:141], v17 offset:80
	ds_read_b128 v[142:145], v17 offset:96
	ds_read_b128 v[146:149], v17 offset:112
	ds_read_b128 v[150:153], v17 offset:128
	s_waitcnt lgkmcnt(8)
	v_mad_u64_u32 v[22:23], s[0:1], v118, 3, 0
	v_mov_b32_e32 v24, v23
	v_mad_u64_u32 v[24:25], s[0:1], v119, 3, v[24:25]
	s_waitcnt lgkmcnt(7)
	v_sub_co_u32_e32 v22, vcc, v22, v122
	v_mov_b64_e32 v[156:157], v[84:85]
	s_nop 0
	v_subb_co_u32_e32 v23, vcc, v24, v123, vcc
	s_waitcnt lgkmcnt(5)
	v_lshl_add_u64 v[202:203], v[22:23], 0, v[130:131]
	v_mad_u64_u32 v[22:23], s[0:1], v120, 3, 0
	v_mov_b32_e32 v24, v23
	v_mad_u64_u32 v[24:25], s[0:1], v121, 3, v[24:25]
	v_sub_co_u32_e32 v22, vcc, v22, v124
	s_movk_i32 s0, 0xfec0
	v_or_b32_e32 v17, 0xffffffe4, v20
	v_or_b32_e32 v226, s57, v20
	v_or3_b32 v227, s56, v20, -16
	v_lshlrev_b32_e32 v20, 4, v225
	v_add_u32_e32 v230, 2, v223
	v_subb_co_u32_e32 v23, vcc, v24, v125, vcc
	v_or3_b32 v234, v190, v21, s0
	v_lshl_add_u64 v[206:207], v[18:19], 1, s[50:51]
	v_mov_b32_e32 v21, v191
	v_mov_b32_e32 v18, 0
	v_mov_b64_e32 v[154:155], v[82:83]
	v_lshl_add_u32 v200, v223, 4, 0
	v_add_u32_e32 v228, s93, v20
	v_add_u32_e32 v229, s57, v223
	v_add_u32_e32 v231, s57, v230
	v_lshl_add_u64 v[204:205], v[22:23], 0, v[132:133]
	v_subrev_u32_e32 v232, 26, v223
	s_mov_b32 s56, 10
	v_lshl_add_u32 v233, v223, 10, v214
	v_lshl_add_u64 v[208:209], s[52:53], 0, v[20:21]
	s_mov_b32 s8, 0
	s_mov_b64 s[0:1], s[60:61]
	v_mov_b32_e32 v19, v18
	v_mov_b32_e32 v20, v18
	v_mov_b32_e32 v21, v18
	v_mov_b32_e32 v22, v18
	v_mov_b32_e32 v23, v18
	v_mov_b32_e32 v24, v18
	v_mov_b32_e32 v25, v18
	v_mov_b32_e32 v26, v18
	v_mov_b32_e32 v27, v18
	v_mov_b32_e32 v28, v18
	v_mov_b32_e32 v29, v18
	v_mov_b32_e32 v30, v18
	v_mov_b32_e32 v31, v18
	v_mov_b32_e32 v32, v18
	v_mov_b32_e32 v33, v18
	v_mov_b32_e32 v34, v18
	v_mov_b32_e32 v35, v18
	v_mov_b32_e32 v36, v18
	v_mov_b32_e32 v37, v18
	v_mov_b32_e32 v38, v18
	v_mov_b32_e32 v39, v18
	v_mov_b32_e32 v40, v18
	v_mov_b32_e32 v41, v18
	v_mov_b32_e32 v42, v18
	v_mov_b32_e32 v43, v18
	v_mov_b32_e32 v44, v18
	v_mov_b32_e32 v45, v18
	v_mov_b32_e32 v46, v18
	v_mov_b32_e32 v47, v18
	v_mov_b32_e32 v48, v18
	v_mov_b32_e32 v49, v18
	v_mov_b32_e32 v50, v18
	v_mov_b32_e32 v51, v18
	v_mov_b32_e32 v52, v18
	v_mov_b32_e32 v53, v18
	v_mov_b32_e32 v54, v18
	v_mov_b32_e32 v55, v18
	v_mov_b32_e32 v56, v18
	v_mov_b32_e32 v57, v18
	v_mov_b32_e32 v58, v18
	v_mov_b32_e32 v59, v18
	v_mov_b32_e32 v60, v18
	v_mov_b32_e32 v61, v18
	v_mov_b32_e32 v62, v18
	v_mov_b32_e32 v63, v18
	v_mov_b32_e32 v64, v18
	v_mov_b32_e32 v65, v18
	v_mul_lo_u32 v245, v234, s71
	v_add_u32_e32 v245, v245, v200
	s_branch .LBB0_438

; #define LAS __attribute__((address_space(3)))
; __device__ __forceinline__ void attn_load_k(const AttnP& P, LAS unsigned char* lds, int hb, int tt, int c, int R0, int lane, bf16x8 (&kf)[4]) {
;     ...
;     } else {
;         const LAS unsigned char* kp = lds + LDS_KC + ((tt - 10) * 32 + 8 * gk_ + pk_) * KC_PITCH + 16 * h;
; #pragma unroll
;         for (int kk = 0; kk < 4; ++kk) kf[kk] = *(const LAS bf16x8*)(kp + 32 * kk);
.LBB0_440:
	s_andn2_b64 vcc, exec, s[4:5]
	s_cbranch_vccnz .LBB0_445
	s_cmp_gt_i32 s56, 9
	s_cselect_b64 s[0:1], -1, 0
	s_mov_b64 s[4:5], -1
	s_and_b64 vcc, exec, s[0:1]
	s_cbranch_vccz .LBB0_476
	s_mul_i32 s4, s56, 0x1400
	v_add_u32_e32 v70, s4, v245
	ds_read_b128 v[66:69], v70
	ds_read_b128 v[178:181], v70 offset:32
	ds_read_b128 v[174:177], v70 offset:64
	ds_read_b128 v[182:185], v70 offset:96
	s_cbranch_execz .LBB0_477

; __device__ __forceinline__ void run_desc(int tt, int g, int c, int R0, int& cg, int& Rg) {
;     if (tt < 4) { cg = c; Rg = R0 - 16 + 4 * tt + g; }
;     else if (tt < 7) { cg = (c + 4 * (tt - 3)) & 15; Rg = R0 - 4 + g; }
;     else if (tt < 10) { const int o = 4 * (tt - 7) + g; const int o3 = (o * 11) >> 5; cg = (c + 1 + o3 * 4 + (o - 3 * o3)) & 15; Rg = R0 - 1; }
;     else { cg = tt - 10; Rg = R0 + g; }
; __device__ __forceinline__ void attn_load_v(const AttnP& P, LAS unsigned char* lds, int hb, int tt, int c, int R0, int lane, bf16x8 (&vf)[2][2]) {
;     ...
;         for (int s = 0; s < 2; ++s) { int cg, Rg; run_desc(tt, 2 * s + h, c, R0, cg, Rg);
;             const bf16_t* vp = P.Vt + ((size_t)((hb * 16 + cg) * 16 + Rg) * 64 + rho) * 8;
.LBB0_445:
	s_and_b64 vcc, exec, s[0:1]
	s_cbranch_vccz .LBB0_506
	s_cmp_gt_i32 s24, 3
	s_cselect_b64 s[6:7], -1, 0
	s_lshl_b32 s25, s24, 2
	s_sub_i32 s11, s25, 28
	s_cmp_gt_u32 s24, 6
	s_cselect_b64 s[0:1], -1, 0
	s_add_i32 s4, s25, s70
	s_waitcnt vmcnt(3) lgkmcnt(3)
	v_cndmask_b32_e64 v66, 0, 1, s[0:1]
	s_and_b32 s10, s4, 15
	s_mov_b64 s[8:9], -1
	s_and_b64 vcc, exec, s[6:7]
	v_cmp_ne_u32_e64 s[4:5], 1, v66
	s_cbranch_vccz .LBB0_450
	s_and_b64 vcc, exec, s[4:5]
	v_mov_b32_e32 v67, s10
	v_mov_b32_e32 v66, v229
	s_cbranch_vccnz .LBB0_449
	v_add_u32_e32 v66, s11, v223
	v_mul_u32_u24_e32 v67, 11, v66
	v_lshrrev_b32_e32 v67, 5, v67
	v_add3_u32 v66, v66, s65, v67
	v_and_b32_e32 v67, 15, v66
	v_mov_b32_e32 v66, s48

; __device__ __forceinline__ void run_desc(int tt, int g, int c, int R0, int& cg, int& Rg) {
;     if (tt < 4) { cg = c; Rg = R0 - 16 + 4 * tt + g; }
;     else if (tt < 7) { cg = (c + 4 * (tt - 3)) & 15; Rg = R0 - 4 + g; }
;     else if (tt < 10) { const int o = 4 * (tt - 7) + g; const int o3 = (o * 11) >> 5; cg = (c + 1 + o3 * 4 + (o - 3 * o3)) & 15; Rg = R0 - 1; }
;     else { cg = tt - 10; Rg = R0 + g; }
; __device__ __forceinline__ void attn_load_v(const AttnP& P, LAS unsigned char* lds, int hb, int tt, int c, int R0, int lane, bf16x8 (&vf)[2][2]) {
;     ...
;         for (int s = 0; s < 2; ++s) { int cg, Rg; run_desc(tt, 2 * s + h, c, R0, cg, Rg);
;             const bf16_t* vp = P.Vt + ((size_t)((hb * 16 + cg) * 16 + Rg) * 64 + rho) * 8;
;             vf[0][s] = *(const bf16x8*)(vp); vf[1][s] = *(const bf16x8*)(vp + 32 * 8); }
.LBB0_452:
	v_lshlrev_b32_e32 v67, 4, v67
	v_add3_u32 v66, v67, s20, v66
	v_ashrrev_i32_e32 v67, 31, v66
	v_lshlrev_b64 v[66:67], 10, v[66:67]
	v_lshl_add_u64 v[66:67], v[208:209], 0, v[66:67]
	global_load_dwordx4 v[162:165], v[66:67], off
	s_waitcnt lgkmcnt(2)
	global_load_dwordx4 v[158:161], v[66:67], off offset:512
	s_andn2_b64 vcc, exec, s[6:7]
	s_mov_b64 s[8:9], -1
	s_cbranch_vccnz .LBB0_456
	s_and_b64 vcc, exec, s[4:5]
	v_mov_b32_e32 v67, s10
	v_mov_b32_e32 v66, v231
	s_cbranch_vccnz .LBB0_455
	v_add_u32_e32 v66, s11, v230
	v_mul_u32_u24_e32 v67, 11, v66
	v_lshrrev_b32_e32 v67, 5, v67
	v_add3_u32 v66, v66, s65, v67
	v_and_b32_e32 v67, 15, v66
	v_mov_b32_e32 v66, s48

; __device__ __forceinline__ void run_desc(int tt, int g, int c, int R0, int& cg, int& Rg) {
;     if (tt < 4) { cg = c; Rg = R0 - 16 + 4 * tt + g; }
;     else if (tt < 7) { cg = (c + 4 * (tt - 3)) & 15; Rg = R0 - 4 + g; }
;     else if (tt < 10) { const int o = 4 * (tt - 7) + g; const int o3 = (o * 11) >> 5; cg = (c + 1 + o3 * 4 + (o - 3 * o3)) & 15; Rg = R0 - 1; }
;     else { cg = tt - 10; Rg = R0 + g; }
; __device__ __forceinline__ void attn_task(const AttnP& P, LAS unsigned char* lds, int b, int hd, int qq, int c, float shift, int lane_in) {
;     ...
;             } else {
;                 { int cg, Rg; run_desc(gi, h, c, R0, cg, Rg); w0 = (c > cg) ? mLp : mLn; }
;                 { int cg, Rg; run_desc(gi, 2 + h, c, R0, cg, Rg); w1 = (c > cg) ? mLp : mLn; }
.LBB0_458:
	v_lshlrev_b32_e32 v67, 4, v67
	v_add3_u32 v66, v67, s20, v66
	v_ashrrev_i32_e32 v67, 31, v66
	v_lshlrev_b64 v[66:67], 10, v[66:67]
	v_lshl_add_u64 v[66:67], v[208:209], 0, v[66:67]
	s_waitcnt lgkmcnt(1)
	global_load_dwordx4 v[166:169], v[66:67], off
	s_waitcnt lgkmcnt(0)
	global_load_dwordx4 v[170:173], v[66:67], off offset:512
	s_mov_b64 s[4:5], -1
	s_and_b64 vcc, exec, s[6:7]
	s_cbranch_vccz .LBB0_464
	s_and_b64 vcc, exec, s[0:1]
	s_cbranch_vccz .LBB0_461
	v_add_u32_e32 v66, s11, v223
	v_mul_u32_u24_e32 v67, 11, v66
	v_lshrrev_b32_e32 v67, 5, v67
	v_add3_u32 v66, v66, s65, v67
	v_and_b32_e32 v66, 15, v66
	v_cmp_gt_u32_e32 vcc, s64, v66
	v_add_u32_e32 v66, s25, v232
	v_mul_u32_u24_e32 v67, 11, v66
	v_lshrrev_b32_e32 v67, 5, v67
	v_add3_u32 v66, v66, s65, v67
	v_and_b32_e32 v66, 15, v66
	v_cndmask_b32_e32 v213, v153, v151, vcc
	v_cndmask_b32_e32 v212, v152, v150, vcc
	v_cmp_gt_u32_e32 vcc, s64, v66
	s_mov_b64 s[4:5], 0
	s_nop 0
	v_cndmask_b32_e32 v211, v153, v151, vcc
	v_cndmask_b32_e32 v210, v152, v150, vcc

; __device__ __forceinline__ void run_desc(int tt, int g, int c, int R0, int& cg, int& Rg) {
;     if (tt < 4) { cg = c; Rg = R0 - 16 + 4 * tt + g; }
;     else if (tt < 7) { cg = (c + 4 * (tt - 3)) & 15; Rg = R0 - 4 + g; }
;     else if (tt < 10) { const int o = 4 * (tt - 7) + g; const int o3 = (o * 11) >> 5; cg = (c + 1 + o3 * 4 + (o - 3 * o3)) & 15; Rg = R0 - 1; }
;     else { cg = tt - 10; Rg = R0 + g; }
; __device__ __forceinline__ void attn_load_k(const AttnP& P, LAS unsigned char* lds, int hb, int tt, int c, int R0, int lane, bf16x8 (&kf)[4]) {
;     ...
;     if (tt < 10) {
;         int cg, Rg; run_desc(tt, gk_, c, R0, cg, Rg);
;         const bf16_t* kp = P.K + ((size_t)(hb * 16 + cg) * 128 + 8 * Rg + pk_) * 64 + 8 * h;
.LBB0_477:
	s_lshl_b32 s6, s56, 2
	s_cmp_gt_i32 s56, 3
	s_mov_b64 s[4:5], -1
	s_cbranch_scc0 .LBB0_483
	s_cmp_gt_u32 s56, 6
	s_cbranch_scc0 .LBB0_480
	s_waitcnt lgkmcnt(3)
	v_add_u32_e32 v66, s6, v17
	v_mul_u32_u24_e32 v67, 11, v66
	v_lshrrev_b32_e32 v67, 5, v67
	v_add3_u32 v66, v66, s65, v67
	v_and_b32_e32 v66, 15, v66
	s_mov_b64 s[4:5], 0

; __device__ __forceinline__ void run_desc(int tt, int g, int c, int R0, int& cg, int& Rg) {
;     if (tt < 4) { cg = c; Rg = R0 - 16 + 4 * tt + g; }
;     else if (tt < 7) { cg = (c + 4 * (tt - 3)) & 15; Rg = R0 - 4 + g; }
;     else if (tt < 10) { const int o = 4 * (tt - 7) + g; const int o3 = (o * 11) >> 5; cg = (c + 1 + o3 * 4 + (o - 3 * o3)) & 15; Rg = R0 - 1; }
;     else { cg = tt - 10; Rg = R0 + g; }
; __device__ __forceinline__ void attn_load_v(const AttnP& P, LAS unsigned char* lds, int hb, int tt, int c, int R0, int lane, bf16x8 (&vf)[2][2]) {
;     ...
;         for (int s = 0; s < 2; ++s) { int cg, Rg; run_desc(tt, 2 * s + h, c, R0, cg, Rg);
;             const bf16_t* vp = P.Vt + ((size_t)((hb * 16 + cg) * 16 + Rg) * 64 + rho) * 8;
.LBB0_487:
	s_cmp_gt_i32 s56, 3
	s_cselect_b64 s[0:1], -1, 0
	s_lshl_b32 s11, s56, 2
	s_sub_i32 s9, s11, 28
	s_cmp_gt_u32 s56, 6
	s_cselect_b64 s[4:5], -1, 0
	s_add_i32 s6, s11, s70
	v_cndmask_b32_e64 v70, 0, 1, s[4:5]
	s_and_b32 s10, s6, 15
	s_mov_b64 s[6:7], -1
	s_and_b64 vcc, exec, s[0:1]
	v_cmp_ne_u32_e64 s[4:5], 1, v70
	s_cbranch_vccz .LBB0_491
	s_and_b64 vcc, exec, s[4:5]
	v_mov_b32_e32 v71, s10
	v_mov_b32_e32 v70, v229
	s_cbranch_vccnz .LBB0_490
	v_add_u32_e32 v70, s9, v223
	v_mul_u32_u24_e32 v71, 11, v70
	v_lshrrev_b32_e32 v71, 5, v71
	v_add3_u32 v70, v70, s65, v71
	v_and_b32_e32 v71, 15, v70
	v_mov_b32_e32 v70, s48

; __device__ __forceinline__ void run_desc(int tt, int g, int c, int R0, int& cg, int& Rg) {
;     if (tt < 4) { cg = c; Rg = R0 - 16 + 4 * tt + g; }
;     else if (tt < 7) { cg = (c + 4 * (tt - 3)) & 15; Rg = R0 - 4 + g; }
;     else if (tt < 10) { const int o = 4 * (tt - 7) + g; const int o3 = (o * 11) >> 5; cg = (c + 1 + o3 * 4 + (o - 3 * o3)) & 15; Rg = R0 - 1; }
;     else { cg = tt - 10; Rg = R0 + g; }
; __device__ __forceinline__ void attn_load_v(const AttnP& P, LAS unsigned char* lds, int hb, int tt, int c, int R0, int lane, bf16x8 (&vf)[2][2]) {
;     ...
;         for (int s = 0; s < 2; ++s) { int cg, Rg; run_desc(tt, 2 * s + h, c, R0, cg, Rg);
;             const bf16_t* vp = P.Vt + ((size_t)((hb * 16 + cg) * 16 + Rg) * 64 + rho) * 8;
;             vf[0][s] = *(const bf16x8*)(vp); vf[1][s] = *(const bf16x8*)(vp + 32 * 8); }
.LBB0_493:
	v_lshlrev_b32_e32 v71, 4, v71
	v_add3_u32 v70, v71, s20, v70
	v_ashrrev_i32_e32 v71, 31, v70
	v_lshlrev_b64 v[70:71], 10, v[70:71]
	v_lshl_add_u64 v[70:71], v[208:209], 0, v[70:71]
	s_waitcnt lgkmcnt(3)
	global_load_dwordx4 v[162:165], v[70:71], off
	s_waitcnt lgkmcnt(2)
	global_load_dwordx4 v[158:161], v[70:71], off offset:512
	s_andn2_b64 vcc, exec, s[0:1]
	s_mov_b64 s[0:1], -1
	s_cbranch_vccnz .LBB0_497
	s_and_b64 vcc, exec, s[4:5]
	v_mov_b32_e32 v71, s10
	v_mov_b32_e32 v70, v231
	s_cbranch_vccnz .LBB0_496
	v_add_u32_e32 v70, s9, v230
	v_mul_u32_u24_e32 v71, 11, v70
	v_lshrrev_b32_e32 v71, 5, v71
	v_add3_u32 v70, v70, s65, v71
	v_and_b32_e32 v71, 15, v70
	v_mov_b32_e32 v70, s48

; __device__ __forceinline__ void attn_task(const AttnP& P, LAS unsigned char* lds, int b, int hd, int qq, int c, float shift, int lane_in) {
;     ...
;             const int dl = c - (li - 10);
;             if (dl == 0) { w0 = 3 * Hp[0] - Hn[0] + Bn[0]; w1 = 3 * Hp[1] - Hn[1] + Bn[1]; }
;             else if (dl > 0) { const unsigned long long m = ((dl & 3) == 0) ? ~0ull : 0ull; w0 = Bp[0] + (Hp[0] & m); w1 = Bp[1] + (Hp[1] & m); }
;             else { const unsigned long long m = ((dl & 3) == 0) ? ~0ull : 0ull; w0 = Bn[0] + (Hn[0] & m); w1 = Bn[1] + (Hn[1] & m); }
.LBB0_500:
	s_add_i32 s0, s56, -10
	s_cmp_eq_u32 s64, s0
	s_cbranch_scc1 .Latb3_own
	s_sub_i32 s4, s64, s0
	s_and_b32 s0, s4, 3
	s_cmp_lg_u32 s0, 0
	s_cbranch_scc1 .Latb3_pure
	s_cmp_lt_i32 s4, 1
	s_mov_b64 s[4:5], -1
	s_cbranch_scc0 .LBB0_503
	v_lshl_add_u64 v[212:213], v[122:123], 0, v[130:131]
	v_lshl_add_u64 v[210:211], v[124:125], 0, v[132:133]
	s_mov_b64 s[4:5], 0

; #define LAS __attribute__((address_space(3)))
; __device__ __forceinline__ int next_tile(int tt, int R0) { while (tt < 26 && !tile_valid(tt, R0)) ++tt; return tt; }
; __device__ __forceinline__ void attn_load_k(const AttnP& P, LAS unsigned char* lds, int hb, int tt, int c, int R0, int lane, bf16x8 (&kf)[4]) {
;     const int rho = lane & 31, h = lane >> 5;
;     const int gk_ = 2 * (rho >> 4) + ((rho >> 2) & 1), pk_ = 4 * ((rho >> 3) & 1) + (rho & 3);
;     if (tt < 10) {
;         int cg, Rg; run_desc(tt, gk_, c, R0, cg, Rg);
;         const bf16_t* kp = P.K + ((size_t)(hb * 16 + cg) * 128 + 8 * Rg + pk_) * 64 + 8 * h;
; #pragma unroll
;         for (int kk = 0; kk < 4; ++kk) kf[kk] = *(const bf16x8*)(kp + 16 * kk);
; __device__ __forceinline__ void attn_task(const AttnP& P, LAS unsigned char* lds, int b, int hd, int qq, int c, float shift, int lane_in) {
;     ...
;             gi = next_tile(gi + 1, R0);
;             if (gi < 10) attn_load_k(P, lds, hb, gi, c, R0, lane, gk);
.LBB0_520:
	v_mov_b64_e32 v[70:71], v[106:107]
	s_waitcnt vmcnt(6)
	v_mov_b64_e32 v[74:75], v[110:111]
	s_waitcnt vmcnt(5)
	v_mov_b64_e32 v[78:79], v[114:115]
	s_waitcnt vmcnt(4)
	v_mov_b64_e32 v[188:189], v[104:105]
	s_cmp_gt_i32 s28, 9
	v_mov_b64_e32 v[72:73], v[108:109]
	v_mov_b64_e32 v[76:77], v[112:113]
	v_mov_b64_e32 v[80:81], v[116:117]
	v_mov_b64_e32 v[186:187], v[102:103]
	s_cbranch_scc1 .LBB0_530
	s_lshl_b32 s4, s28, 2
	s_cmp_gt_i32 s28, 3
	s_mov_b64 s[0:1], -1
	s_cbranch_scc0 .LBB0_527
	s_cmp_gt_u32 s28, 6
	s_cbranch_scc0 .LBB0_524
	v_add_u32_e32 v66, s4, v17
	v_mul_u32_u24_e32 v67, 11, v66
	v_lshrrev_b32_e32 v67, 5, v67
	v_add3_u32 v66, v66, s65, v67
	v_and_b32_e32 v66, 15, v66
	s_mov_b64 s[0:1], 0
